# GEMM mainloops: first K iteration peeled with C=0 so the per-tile accumulator zeroing moves are gone
# speedup vs baseline: 1.0200x; 1.0106x over previous
; #define PG8_STAGE(bufoff, gbase, voff) do { _Pragma("unroll") for (int _i = 0; _i < 2; ++_i) \
;         __builtin_amdgcn_global_load_lds((const unsigned*)((const char*)(gbase) + (voff)[_i]), (LAS unsigned*)(lds + (bufoff) + ldsw + _i * 8192), 16, 0, 0); } while (0)
; #define PG8_LDA(dst, b, h) do { _Pragma("unroll") for (int m = 0; m < 4; ++m) _Pragma("unroll") for (int k = 0; k < 2; ++k) dst[m][k] = *(const LAS bf16x8*)(lds + PG8_SA(b, h) + aoff + m * 2048 + k * 1024); } while (0)
; #define PG8_LDB(dst, b, h) do { _Pragma("unroll") for (int n = 0; n < 2; ++n) _Pragma("unroll") for (int k = 0; k < 2; ++k) dst[n][k] = *(const LAS bf16x8*)(lds + PG8_SB(b, h) + boff + n * 2048 + k * 1024); } while (0)
; #define PG8_MMA(ai, bj, At, Bt) do { __builtin_amdgcn_s_setprio(1); _Pragma("unroll") for (int m = 0; m < 4; ++m) _Pragma("unroll") for (int n = 0; n < 2; ++n) _Pragma("unroll") for (int k = 0; k < 2; ++k) \
;         acc[ai][bj][m][n] = __builtin_amdgcn_mfma_f32_16x16x32_bf16(Bt[n][k], At[m][k], acc[ai][bj][m][n], 0, 0, 0); __builtin_amdgcn_s_setprio(0); } while (0)
; #define PG8_WAIT_V(n) asm volatile("s_waitcnt vmcnt(" #n ")" ::: "memory")
; #define PG8_WAIT_L(n) asm volatile("s_waitcnt lgkmcnt(" #n ")" ::: "memory")
; #define PG8_BAR __builtin_amdgcn_s_barrier()
; #define PG8_SCHED __builtin_amdgcn_sched_barrier(0)
; __device__ __forceinline__ void gemm_phase(LAS unsigned char* lds, const Gemm g, const StaticOrder& S, const LAS Epi* Ep, const int tid) {
;     ...
;         for (int t = 0; t < nt; t += 2) {
;             const bool last = (t == nt - 2);
;             const char* a1 = cA + (size_t)(t + 1) * kstep;
;             const char* a2 = last ? nA : cA + (size_t)(t + 2) * kstep; const char* b2 = last ? nB : cB + (size_t)(t + 2) * kstep;
;             const char* a3 = a2 + kstep; const char* b3 = b2 + kstep;
;             PG8_LDB(B0, 0, 0); PG8_LDB(B1, 0, 1); PG8_SCHED; PG8_LDA(At, 0, 0); PG8_STAGE(PG8_SA(1, 1), a1 + hstepA, voffA);
;             PG8_WAIT_V(8); PG8_WAIT_L(0); PG8_BAR; PG8_MMA(0, 0, At, B0); PG8_MMA(0, 1, At, B1); PG8_BAR; PG8_SCHED;
;             PG8_LDA(At, 0, 1); PG8_STAGE(PG8_SB(0, 0), b2, voffB); PG8_STAGE(PG8_SB(0, 1), b2 + hstepB, voffB); PG8_STAGE(PG8_SA(0, 0), a2, voffA);
.LBB0_406:
	s_add_u32 s0, s0, 0x80
	s_addc_u32 s1, s1, 0
	s_add_u32 s3, s14, 0x100
	s_addc_u32 s16, s15, 0
	s_mov_b32 s14, 0
	s_add_i32 s17, s14, 2
	s_add_u32 s18, s0, 0x80
	s_addc_u32 s15, s1, 0
	s_add_i32 s20, 0, 0x10000
	s_cmp_eq_u32 s66, s14
	s_cselect_b32 s15, s11, s15
	s_cselect_b32 s14, s10, s18
	v_add_u32_e32 v2, s20, v233
	s_cselect_b32 s19, s13, s16
	s_cselect_b32 s18, s12, s3
	s_add_i32 s21, 0, 0x14000
	s_waitcnt lgkmcnt(0)
	ds_read_b128 v[132:135], v2
	ds_read_b128 v[136:139], v2 offset:1024
	ds_read_b128 v[140:143], v2 offset:2048
	ds_read_b128 v[144:147], v2 offset:3072
	v_add_u32_e32 v2, s21, v233
	ds_read_b128 v[148:151], v2
	ds_read_b128 v[152:155], v2 offset:1024
	ds_read_b128 v[156:159], v2 offset:2048
	ds_read_b128 v[160:163], v2 offset:3072
	v_lshl_add_u64 v[210:211], s[0:1], 0, v[206:207]
	s_add_i32 m0, s78, 0xc000
	ds_read_b128 v[164:167], v235
	ds_read_b128 v[168:171], v235 offset:1024
	ds_read_b128 v[172:175], v235 offset:2048
	ds_read_b128 v[176:179], v235 offset:3072
	ds_read_b128 v[180:183], v235 offset:4096
	ds_read_b128 v[184:187], v235 offset:5120
	ds_read_b128 v[188:191], v235 offset:6144
	ds_read_b128 v[192:195], v235 offset:7168
	global_load_lds_dwordx4 v[210:211], off
	v_lshl_add_u64 v[210:211], s[0:1], 0, v[208:209]
	s_add_i32 m0, s78, 0xe000
	s_nop 0
	global_load_lds_dwordx4 v[210:211], off
	s_waitcnt vmcnt(8)
	s_waitcnt lgkmcnt(0)
	s_barrier
	s_setprio 1
	s_waitcnt lgkmcnt(0)
	v_mfma_f32_16x16x32_bf16 v[128:131], v[132:135], v[164:167], 0
	v_mfma_f32_16x16x32_bf16 v[120:123], v[140:143], v[164:167], 0
	v_mfma_f32_16x16x32_bf16 v[112:115], v[132:135], v[172:175], 0
	v_mfma_f32_16x16x32_bf16 v[104:107], v[140:143], v[172:175], 0
	v_mfma_f32_16x16x32_bf16 v[96:99], v[132:135], v[180:183], 0
	v_mfma_f32_16x16x32_bf16 v[88:91], v[140:143], v[180:183], 0
	v_mfma_f32_16x16x32_bf16 v[80:83], v[132:135], v[188:191], 0
	v_mfma_f32_16x16x32_bf16 v[72:75], v[140:143], v[188:191], 0
	v_mfma_f32_16x16x32_bf16 v[128:131], v[136:139], v[168:171], v[128:131]
	v_mfma_f32_16x16x32_bf16 v[120:123], v[144:147], v[168:171], v[120:123]
	v_mfma_f32_16x16x32_bf16 v[112:115], v[136:139], v[176:179], v[112:115]
	v_mfma_f32_16x16x32_bf16 v[104:107], v[144:147], v[176:179], v[104:107]
	v_mfma_f32_16x16x32_bf16 v[96:99], v[136:139], v[184:187], v[96:99]
	v_mfma_f32_16x16x32_bf16 v[88:91], v[144:147], v[184:187], v[88:91]
	v_mfma_f32_16x16x32_bf16 v[80:83], v[136:139], v[192:195], v[80:83]
	v_mfma_f32_16x16x32_bf16 v[72:75], v[144:147], v[192:195], v[72:75]
	s_setprio 0
	s_setprio 1
	v_mfma_f32_16x16x32_bf16 v[124:127], v[148:151], v[164:167], 0
	v_mfma_f32_16x16x32_bf16 v[116:119], v[156:159], v[164:167], 0
	v_mfma_f32_16x16x32_bf16 v[108:111], v[148:151], v[172:175], 0
	v_mfma_f32_16x16x32_bf16 v[100:103], v[156:159], v[172:175], 0
	v_mfma_f32_16x16x32_bf16 v[92:95], v[148:151], v[180:183], 0
	v_mfma_f32_16x16x32_bf16 v[84:87], v[156:159], v[180:183], 0
	v_mfma_f32_16x16x32_bf16 v[76:79], v[148:151], v[188:191], 0
	v_mfma_f32_16x16x32_bf16 v[68:71], v[156:159], v[188:191], 0
	v_mfma_f32_16x16x32_bf16 v[124:127], v[152:155], v[168:171], v[124:127]
	v_mfma_f32_16x16x32_bf16 v[116:119], v[160:163], v[168:171], v[116:119]
	v_mfma_f32_16x16x32_bf16 v[108:111], v[152:155], v[176:179], v[108:111]
	v_mfma_f32_16x16x32_bf16 v[100:103], v[160:163], v[176:179], v[100:103]
	v_mfma_f32_16x16x32_bf16 v[92:95], v[152:155], v[184:187], v[92:95]
	v_mfma_f32_16x16x32_bf16 v[84:87], v[160:163], v[184:187], v[84:87]
	v_mfma_f32_16x16x32_bf16 v[76:79], v[152:155], v[192:195], v[76:79]
	v_mfma_f32_16x16x32_bf16 v[68:71], v[160:163], v[192:195], v[68:71]
	s_setprio 0
	s_barrier
	s_add_i32 s20, s20, s85
	v_lshl_add_u64 v[210:211], s[18:19], 0, v[196:197]
	s_mov_b32 m0, s20
	ds_read_b128 v[164:167], v235 offset:16384
	ds_read_b128 v[168:171], v235 offset:17408
	ds_read_b128 v[172:175], v235 offset:18432
	ds_read_b128 v[176:179], v235 offset:19456
	ds_read_b128 v[180:183], v235 offset:20480
	ds_read_b128 v[184:187], v235 offset:21504
	ds_read_b128 v[188:191], v235 offset:22528
	ds_read_b128 v[192:195], v235 offset:23552
	global_load_lds_dwordx4 v[210:211], off
	s_add_i32 m0, s20, 0x2000
	v_lshl_add_u64 v[212:213], s[18:19], 0, v[200:201]
	s_add_u32 s18, s18, s39
	s_addc_u32 s19, s19, 0
	s_add_i32 s20, s21, s85
	global_load_lds_dwordx4 v[212:213], off
	v_lshl_add_u64 v[214:215], s[18:19], 0, v[196:197]
	s_mov_b32 m0, s20
	v_lshl_add_u64 v[216:217], s[18:19], 0, v[200:201]
	global_load_lds_dwordx4 v[214:215], off
	s_add_i32 m0, s20, 0x2000
	v_lshl_add_u64 v[218:219], s[14:15], 0, v[0:1]
	global_load_lds_dwordx4 v[216:217], off
	s_mov_b32 m0, s78
	v_lshl_add_u64 v[220:221], s[14:15], 0, v[198:199]
	global_load_lds_dwordx4 v[218:219], off
	s_mov_b32 m0, s56
	s_nop 0
	global_load_lds_dwordx4 v[220:221], off
	s_waitcnt vmcnt(8)
	s_waitcnt lgkmcnt(0)
	s_barrier
; #define PG8_STAGE(bufoff, gbase, voff) do { _Pragma("unroll") for (int _i = 0; _i < 2; ++_i) \
;         __builtin_amdgcn_global_load_lds((const unsigned*)((const char*)(gbase) + (voff)[_i]), (LAS unsigned*)(lds + (bufoff) + ldsw + _i * 8192), 16, 0, 0); } while (0)
; #define PG8_LDA(dst, b, h) do { _Pragma("unroll") for (int m = 0; m < 4; ++m) _Pragma("unroll") for (int k = 0; k < 2; ++k) dst[m][k] = *(const LAS bf16x8*)(lds + PG8_SA(b, h) + aoff + m * 2048 + k * 1024); } while (0)
; #define PG8_LDB(dst, b, h) do { _Pragma("unroll") for (int n = 0; n < 2; ++n) _Pragma("unroll") for (int k = 0; k < 2; ++k) dst[n][k] = *(const LAS bf16x8*)(lds + PG8_SB(b, h) + boff + n * 2048 + k * 1024); } while (0)
; #define PG8_MMA(ai, bj, At, Bt) do { __builtin_amdgcn_s_setprio(1); _Pragma("unroll") for (int m = 0; m < 4; ++m) _Pragma("unroll") for (int n = 0; n < 2; ++n) _Pragma("unroll") for (int k = 0; k < 2; ++k) \
;         acc[ai][bj][m][n] = __builtin_amdgcn_mfma_f32_16x16x32_bf16(Bt[n][k], At[m][k], acc[ai][bj][m][n], 0, 0, 0); __builtin_amdgcn_s_setprio(0); } while (0)
; #define PG8_WAIT_V(n) asm volatile("s_waitcnt vmcnt(" #n ")" ::: "memory")
; #define PG8_WAIT_L(n) asm volatile("s_waitcnt lgkmcnt(" #n ")" ::: "memory")
; #define PG8_BAR __builtin_amdgcn_s_barrier()
; #define PG8_SCHED __builtin_amdgcn_sched_barrier(0)
; __device__ __forceinline__ void gemm_phase(LAS unsigned char* lds, const Gemm g, const StaticOrder& S, const LAS Epi* Ep, const int tid) {
;     ...
;             PG8_WAIT_V(8); PG8_WAIT_L(0); PG8_BAR; PG8_MMA(1, 0, At, B0); PG8_MMA(1, 1, At, B1); PG8_BAR; PG8_SCHED;
;             PG8_LDB(B0, 1, 0); PG8_LDB(B1, 1, 1); PG8_SCHED; PG8_LDA(At, 1, 0); PG8_STAGE(PG8_SA(0, 1), a2 + hstepA, voffA);
;             PG8_WAIT_V(8); PG8_WAIT_L(0); PG8_BAR; PG8_MMA(0, 0, At, B0); PG8_MMA(0, 1, At, B1); PG8_BAR; PG8_SCHED;
	s_setprio 1
	s_waitcnt lgkmcnt(0)
	v_mfma_f32_16x16x32_bf16 v[64:67], v[132:135], v[164:167], 0
	v_mfma_f32_16x16x32_bf16 v[56:59], v[140:143], v[164:167], 0
	v_mfma_f32_16x16x32_bf16 v[48:51], v[132:135], v[172:175], 0
	v_mfma_f32_16x16x32_bf16 v[40:43], v[140:143], v[172:175], 0
	v_mfma_f32_16x16x32_bf16 v[32:35], v[132:135], v[180:183], 0
	v_mfma_f32_16x16x32_bf16 v[24:27], v[140:143], v[180:183], 0
	v_mfma_f32_16x16x32_bf16 v[16:19], v[132:135], v[188:191], 0
	v_mfma_f32_16x16x32_bf16 v[8:11], v[140:143], v[188:191], 0
	v_mfma_f32_16x16x32_bf16 v[64:67], v[136:139], v[168:171], v[64:67]
	v_mfma_f32_16x16x32_bf16 v[56:59], v[144:147], v[168:171], v[56:59]
	v_mfma_f32_16x16x32_bf16 v[48:51], v[136:139], v[176:179], v[48:51]
	v_mfma_f32_16x16x32_bf16 v[40:43], v[144:147], v[176:179], v[40:43]
	v_mfma_f32_16x16x32_bf16 v[32:35], v[136:139], v[184:187], v[32:35]
	v_mfma_f32_16x16x32_bf16 v[24:27], v[144:147], v[184:187], v[24:27]
	v_mfma_f32_16x16x32_bf16 v[16:19], v[136:139], v[192:195], v[16:19]
	v_mfma_f32_16x16x32_bf16 v[8:11], v[144:147], v[192:195], v[8:11]
	s_setprio 0
	s_setprio 1
	v_mfma_f32_16x16x32_bf16 v[60:63], v[148:151], v[164:167], 0
	v_mfma_f32_16x16x32_bf16 v[52:55], v[156:159], v[164:167], 0
	v_mfma_f32_16x16x32_bf16 v[44:47], v[148:151], v[172:175], 0
	v_mfma_f32_16x16x32_bf16 v[36:39], v[156:159], v[172:175], 0
	v_mfma_f32_16x16x32_bf16 v[28:31], v[148:151], v[180:183], 0
	v_mfma_f32_16x16x32_bf16 v[20:23], v[156:159], v[180:183], 0
	v_mfma_f32_16x16x32_bf16 v[12:15], v[148:151], v[188:191], 0
	v_mfma_f32_16x16x32_bf16 v[4:7], v[156:159], v[188:191], 0
	v_mfma_f32_16x16x32_bf16 v[60:63], v[152:155], v[168:171], v[60:63]
	v_mfma_f32_16x16x32_bf16 v[52:55], v[160:163], v[168:171], v[52:55]
	v_mfma_f32_16x16x32_bf16 v[44:47], v[152:155], v[176:179], v[44:47]
	v_mfma_f32_16x16x32_bf16 v[36:39], v[160:163], v[176:179], v[36:39]
	v_mfma_f32_16x16x32_bf16 v[28:31], v[152:155], v[184:187], v[28:31]
	v_mfma_f32_16x16x32_bf16 v[20:23], v[160:163], v[184:187], v[20:23]
	v_mfma_f32_16x16x32_bf16 v[12:15], v[152:155], v[192:195], v[12:15]
	v_mfma_f32_16x16x32_bf16 v[4:7], v[160:163], v[192:195], v[4:7]
	s_setprio 0
	s_barrier
	s_add_i32 s18, 0, 0x18000
	v_add_u32_e32 v2, s18, v233
	s_add_i32 s19, 0, 0x1c000
	ds_read_b128 v[132:135], v2
	ds_read_b128 v[136:139], v2 offset:1024
	ds_read_b128 v[140:143], v2 offset:2048
	ds_read_b128 v[144:147], v2 offset:3072
	v_add_u32_e32 v2, s19, v233
	ds_read_b128 v[148:151], v2
	ds_read_b128 v[152:155], v2 offset:1024
	ds_read_b128 v[156:159], v2 offset:2048
	ds_read_b128 v[160:163], v2 offset:3072
	s_add_u32 s14, s14, s86
	s_addc_u32 s15, s15, 0
	s_mov_b32 m0, s57
	v_lshl_add_u64 v[222:223], s[14:15], 0, v[0:1]
	ds_read_b128 v[164:167], v235 offset:32768
	ds_read_b128 v[168:171], v235 offset:33792
	ds_read_b128 v[172:175], v235 offset:34816
	ds_read_b128 v[176:179], v235 offset:35840
	ds_read_b128 v[180:183], v235 offset:36864
	ds_read_b128 v[184:187], v235 offset:37888
	ds_read_b128 v[188:191], v235 offset:38912
	ds_read_b128 v[192:195], v235 offset:39936
	global_load_lds_dwordx4 v[222:223], off
	v_lshl_add_u64 v[222:223], s[14:15], 0, v[198:199]
	s_mov_b32 m0, s58
	s_nop 0
	global_load_lds_dwordx4 v[222:223], off
	s_waitcnt vmcnt(8)
	s_waitcnt lgkmcnt(0)
	s_barrier
	s_setprio 1
	s_waitcnt lgkmcnt(0)
	v_mfma_f32_16x16x32_bf16 v[128:131], v[132:135], v[164:167], v[128:131]
	v_mfma_f32_16x16x32_bf16 v[120:123], v[140:143], v[164:167], v[120:123]
	v_mfma_f32_16x16x32_bf16 v[112:115], v[132:135], v[172:175], v[112:115]
	v_mfma_f32_16x16x32_bf16 v[104:107], v[140:143], v[172:175], v[104:107]
	v_mfma_f32_16x16x32_bf16 v[96:99], v[132:135], v[180:183], v[96:99]
	v_mfma_f32_16x16x32_bf16 v[88:91], v[140:143], v[180:183], v[88:91]
	v_mfma_f32_16x16x32_bf16 v[80:83], v[132:135], v[188:191], v[80:83]
	v_mfma_f32_16x16x32_bf16 v[72:75], v[140:143], v[188:191], v[72:75]
	v_mfma_f32_16x16x32_bf16 v[128:131], v[136:139], v[168:171], v[128:131]
	v_mfma_f32_16x16x32_bf16 v[120:123], v[144:147], v[168:171], v[120:123]
	v_mfma_f32_16x16x32_bf16 v[112:115], v[136:139], v[176:179], v[112:115]
	v_mfma_f32_16x16x32_bf16 v[104:107], v[144:147], v[176:179], v[104:107]
	v_mfma_f32_16x16x32_bf16 v[96:99], v[136:139], v[184:187], v[96:99]
	v_mfma_f32_16x16x32_bf16 v[88:91], v[144:147], v[184:187], v[88:91]
	v_mfma_f32_16x16x32_bf16 v[80:83], v[136:139], v[192:195], v[80:83]
	v_mfma_f32_16x16x32_bf16 v[72:75], v[144:147], v[192:195], v[72:75]
	s_setprio 0
	s_setprio 1
	v_mfma_f32_16x16x32_bf16 v[124:127], v[148:151], v[164:167], v[124:127]
	v_mfma_f32_16x16x32_bf16 v[116:119], v[156:159], v[164:167], v[116:119]
	v_mfma_f32_16x16x32_bf16 v[108:111], v[148:151], v[172:175], v[108:111]
	v_mfma_f32_16x16x32_bf16 v[100:103], v[156:159], v[172:175], v[100:103]
	v_mfma_f32_16x16x32_bf16 v[92:95], v[148:151], v[180:183], v[92:95]
	v_mfma_f32_16x16x32_bf16 v[84:87], v[156:159], v[180:183], v[84:87]
	v_mfma_f32_16x16x32_bf16 v[76:79], v[148:151], v[188:191], v[76:79]
	v_mfma_f32_16x16x32_bf16 v[68:71], v[156:159], v[188:191], v[68:71]
	v_mfma_f32_16x16x32_bf16 v[124:127], v[152:155], v[168:171], v[124:127]
	v_mfma_f32_16x16x32_bf16 v[116:119], v[160:163], v[168:171], v[116:119]
	v_mfma_f32_16x16x32_bf16 v[108:111], v[152:155], v[176:179], v[108:111]
	v_mfma_f32_16x16x32_bf16 v[100:103], v[160:163], v[176:179], v[100:103]
	v_mfma_f32_16x16x32_bf16 v[92:95], v[152:155], v[184:187], v[92:95]
	v_mfma_f32_16x16x32_bf16 v[84:87], v[160:163], v[184:187], v[84:87]
	v_mfma_f32_16x16x32_bf16 v[76:79], v[152:155], v[192:195], v[76:79]
	v_mfma_f32_16x16x32_bf16 v[68:71], v[160:163], v[192:195], v[68:71]
	s_setprio 0
	s_barrier
; #define PG8_STAGE(bufoff, gbase, voff) do { _Pragma("unroll") for (int _i = 0; _i < 2; ++_i) \
;         __builtin_amdgcn_global_load_lds((const unsigned*)((const char*)(gbase) + (voff)[_i]), (LAS unsigned*)(lds + (bufoff) + ldsw + _i * 8192), 16, 0, 0); } while (0)
; #define PG8_LDA(dst, b, h) do { _Pragma("unroll") for (int m = 0; m < 4; ++m) _Pragma("unroll") for (int k = 0; k < 2; ++k) dst[m][k] = *(const LAS bf16x8*)(lds + PG8_SA(b, h) + aoff + m * 2048 + k * 1024); } while (0)
; #define PG8_MMA(ai, bj, At, Bt) do { __builtin_amdgcn_s_setprio(1); _Pragma("unroll") for (int m = 0; m < 4; ++m) _Pragma("unroll") for (int n = 0; n < 2; ++n) _Pragma("unroll") for (int k = 0; k < 2; ++k) \
;         acc[ai][bj][m][n] = __builtin_amdgcn_mfma_f32_16x16x32_bf16(Bt[n][k], At[m][k], acc[ai][bj][m][n], 0, 0, 0); __builtin_amdgcn_s_setprio(0); } while (0)
; #define PG8_WAIT_V(n) asm volatile("s_waitcnt vmcnt(" #n ")" ::: "memory")
; #define PG8_WAIT_L(n) asm volatile("s_waitcnt lgkmcnt(" #n ")" ::: "memory")
; #define PG8_BAR __builtin_amdgcn_s_barrier()
; #define PG8_SCHED __builtin_amdgcn_sched_barrier(0)
; __device__ __forceinline__ void gemm_phase(LAS unsigned char* lds, const Gemm g, const StaticOrder& S, const LAS Epi* Ep, const int tid) {
;     ...
;             PG8_LDA(At, 1, 1); PG8_STAGE(PG8_SB(1, 0), b3, voffB); PG8_STAGE(PG8_SB(1, 1), b3 + hstepB, voffB); PG8_STAGE(PG8_SA(1, 0), a3, voffA);
;             PG8_WAIT_V(8); PG8_WAIT_L(0); PG8_BAR; PG8_MMA(1, 0, At, B0); PG8_MMA(1, 1, At, B1); PG8_BAR; PG8_SCHED;
;         }
	s_add_i32 s14, s18, s85
	v_lshl_add_u64 v[210:211], v[210:211], 0, s[88:89]
	s_mov_b32 m0, s14
	ds_read_b128 v[164:167], v235 offset:49152
	ds_read_b128 v[168:171], v235 offset:50176
	ds_read_b128 v[172:175], v235 offset:51200
	ds_read_b128 v[176:179], v235 offset:52224
	ds_read_b128 v[180:183], v235 offset:53248
	ds_read_b128 v[184:187], v235 offset:54272
	ds_read_b128 v[188:191], v235 offset:55296
	ds_read_b128 v[192:195], v235 offset:56320
	global_load_lds_dwordx4 v[210:211], off
	v_lshl_add_u64 v[210:211], v[212:213], 0, s[88:89]
	s_add_i32 m0, s14, 0x2000
	s_add_i32 s14, s19, s85
	global_load_lds_dwordx4 v[210:211], off
	v_lshl_add_u64 v[210:211], v[214:215], 0, s[88:89]
	s_mov_b32 m0, s14
	s_nop 0
	global_load_lds_dwordx4 v[210:211], off
	v_lshl_add_u64 v[210:211], v[216:217], 0, s[88:89]
	s_add_i32 m0, s14, 0x2000
	s_nop 0
	global_load_lds_dwordx4 v[210:211], off
	v_lshl_add_u64 v[210:211], v[218:219], 0, s[88:89]
	s_mov_b32 m0, s59
	s_nop 0
	global_load_lds_dwordx4 v[210:211], off
	v_lshl_add_u64 v[210:211], v[220:221], 0, s[88:89]
	s_mov_b32 m0, s60
	s_nop 0
	global_load_lds_dwordx4 v[210:211], off
	s_waitcnt vmcnt(8)
	s_waitcnt lgkmcnt(0)
	s_barrier
	s_setprio 1
	s_waitcnt lgkmcnt(0)
	v_mfma_f32_16x16x32_bf16 v[64:67], v[132:135], v[164:167], v[64:67]
	v_mfma_f32_16x16x32_bf16 v[56:59], v[140:143], v[164:167], v[56:59]
	v_mfma_f32_16x16x32_bf16 v[48:51], v[132:135], v[172:175], v[48:51]
	v_mfma_f32_16x16x32_bf16 v[40:43], v[140:143], v[172:175], v[40:43]
	v_mfma_f32_16x16x32_bf16 v[32:35], v[132:135], v[180:183], v[32:35]
	v_mfma_f32_16x16x32_bf16 v[24:27], v[140:143], v[180:183], v[24:27]
	v_mfma_f32_16x16x32_bf16 v[16:19], v[132:135], v[188:191], v[16:19]
	v_mfma_f32_16x16x32_bf16 v[8:11], v[140:143], v[188:191], v[8:11]
	v_mfma_f32_16x16x32_bf16 v[64:67], v[136:139], v[168:171], v[64:67]
	v_mfma_f32_16x16x32_bf16 v[56:59], v[144:147], v[168:171], v[56:59]
	v_mfma_f32_16x16x32_bf16 v[48:51], v[136:139], v[176:179], v[48:51]
	v_mfma_f32_16x16x32_bf16 v[40:43], v[144:147], v[176:179], v[40:43]
	v_mfma_f32_16x16x32_bf16 v[32:35], v[136:139], v[184:187], v[32:35]
	v_mfma_f32_16x16x32_bf16 v[24:27], v[144:147], v[184:187], v[24:27]
	v_mfma_f32_16x16x32_bf16 v[16:19], v[136:139], v[192:195], v[16:19]
	v_mfma_f32_16x16x32_bf16 v[8:11], v[144:147], v[192:195], v[8:11]
	s_setprio 0
	s_setprio 1
	v_mfma_f32_16x16x32_bf16 v[60:63], v[148:151], v[164:167], v[60:63]
	v_mfma_f32_16x16x32_bf16 v[52:55], v[156:159], v[164:167], v[52:55]
	v_mfma_f32_16x16x32_bf16 v[44:47], v[148:151], v[172:175], v[44:47]
	v_mfma_f32_16x16x32_bf16 v[36:39], v[156:159], v[172:175], v[36:39]
	v_mfma_f32_16x16x32_bf16 v[28:31], v[148:151], v[180:183], v[28:31]
	v_mfma_f32_16x16x32_bf16 v[20:23], v[156:159], v[180:183], v[20:23]
	v_mfma_f32_16x16x32_bf16 v[12:15], v[148:151], v[188:191], v[12:15]
	v_mfma_f32_16x16x32_bf16 v[4:7], v[156:159], v[188:191], v[4:7]
	v_mfma_f32_16x16x32_bf16 v[60:63], v[152:155], v[168:171], v[60:63]
	v_mfma_f32_16x16x32_bf16 v[52:55], v[160:163], v[168:171], v[52:55]
	v_mfma_f32_16x16x32_bf16 v[44:47], v[152:155], v[176:179], v[44:47]
	v_mfma_f32_16x16x32_bf16 v[36:39], v[160:163], v[176:179], v[36:39]
	v_mfma_f32_16x16x32_bf16 v[28:31], v[152:155], v[184:187], v[28:31]
	v_mfma_f32_16x16x32_bf16 v[20:23], v[160:163], v[184:187], v[20:23]
	v_mfma_f32_16x16x32_bf16 v[12:15], v[152:155], v[192:195], v[12:15]
	v_mfma_f32_16x16x32_bf16 v[4:7], v[160:163], v[192:195], v[4:7]
	s_setprio 0
	s_barrier
	s_add_u32 s0, s0, 0x100
	s_addc_u32 s1, s1, 0
	s_add_u32 s3, s3, 0x100
	s_addc_u32 s16, s16, 0
	s_cmp_ge_u32 s17, s61
	s_mov_b32 s14, s17
	s_cbranch_scc0 .LBB0_407
	s_branch .Lpeel1_exit

; #define PG8_BAR __builtin_amdgcn_s_barrier()
; __device__ __forceinline__ void gemm_phase(LAS unsigned char* lds, const Gemm g, const StaticOrder& S, const LAS Epi* Ep, const int tid) {
;     ...
;         }
;         if (wr == 0) PG8_BAR;
.Lpeel1_exit:
	s_and_b64 vcc, exec, s[8:9]
	s_cbranch_vccz .LBB0_410
	s_barrier

; #define PG8_STAGE(bufoff, gbase, voff) do { _Pragma("unroll") for (int _i = 0; _i < 2; ++_i) \
;         __builtin_amdgcn_global_load_lds((const unsigned*)((const char*)(gbase) + (voff)[_i]), (LAS unsigned*)(lds + (bufoff) + ldsw + _i * 8192), 16, 0, 0); } while (0)
; #define PG8_LDA(dst, b, h) do { _Pragma("unroll") for (int m = 0; m < 4; ++m) _Pragma("unroll") for (int k = 0; k < 2; ++k) dst[m][k] = *(const LAS bf16x8*)(lds + PG8_SA(b, h) + aoff + m * 2048 + k * 1024); } while (0)
; #define PG8_LDB(dst, b, h) do { _Pragma("unroll") for (int n = 0; n < 2; ++n) _Pragma("unroll") for (int k = 0; k < 2; ++k) dst[n][k] = *(const LAS bf16x8*)(lds + PG8_SB(b, h) + boff + n * 2048 + k * 1024); } while (0)
; #define PG8_MMA(ai, bj, At, Bt) do { __builtin_amdgcn_s_setprio(1); _Pragma("unroll") for (int m = 0; m < 4; ++m) _Pragma("unroll") for (int n = 0; n < 2; ++n) _Pragma("unroll") for (int k = 0; k < 2; ++k) \
;         acc[ai][bj][m][n] = __builtin_amdgcn_mfma_f32_16x16x32_bf16(Bt[n][k], At[m][k], acc[ai][bj][m][n], 0, 0, 0); __builtin_amdgcn_s_setprio(0); } while (0)
; #define PG8_WAIT_V(n) asm volatile("s_waitcnt vmcnt(" #n ")" ::: "memory")
; #define PG8_WAIT_L(n) asm volatile("s_waitcnt lgkmcnt(" #n ")" ::: "memory")
; #define PG8_BAR __builtin_amdgcn_s_barrier()
; #define PG8_SCHED __builtin_amdgcn_sched_barrier(0)
; __device__ __forceinline__ void gemm_phase(LAS unsigned char* lds, const Gemm g, const StaticOrder& S, const LAS Epi* Ep, const int tid) {
;     ...
;         for (int t = 0; t < nt; t += 2) {
;             const bool last = (t == nt - 2);
;             const char* a1 = cA + (size_t)(t + 1) * kstep;
;             const char* a2 = last ? nA : cA + (size_t)(t + 2) * kstep; const char* b2 = last ? nB : cB + (size_t)(t + 2) * kstep;
;             const char* a3 = a2 + kstep; const char* b3 = b2 + kstep;
;             PG8_LDB(B0, 0, 0); PG8_LDB(B1, 0, 1); PG8_SCHED; PG8_LDA(At, 0, 0); PG8_STAGE(PG8_SA(1, 1), a1 + hstepA, voffA);
;             PG8_WAIT_V(8); PG8_WAIT_L(0); PG8_BAR; PG8_MMA(0, 0, At, B0); PG8_MMA(0, 1, At, B1); PG8_BAR; PG8_SCHED;
;             PG8_LDA(At, 0, 1); PG8_STAGE(PG8_SB(0, 0), b2, voffB); PG8_STAGE(PG8_SB(0, 1), b2 + hstepB, voffB); PG8_STAGE(PG8_SA(0, 0), a2, voffA);
.LBB0_1433:
	s_add_u32 s0, s0, 0x80
	s_addc_u32 s1, s1, 0
	s_add_u32 s3, s38, 0x100
	s_addc_u32 s5, s39, 0
	s_mov_b32 s23, 0
	s_waitcnt vmcnt(0)
	s_add_i32 s48, s23, 2
	s_add_u32 s38, s0, 0x80
	s_addc_u32 s39, s1, 0
	s_add_i32 s49, 0, 0x10000
	s_cmp_eq_u32 s20, s23
	s_cselect_b32 s39, s35, s39
	s_cselect_b32 s38, s34, s38
	v_add_u32_e32 v0, s49, v247
	s_cselect_b32 s51, s37, s5
	s_cselect_b32 s50, s36, s3
	s_add_i32 s23, 0, 0x14000
	s_waitcnt lgkmcnt(0)
	ds_read_b128 v[130:133], v0
	ds_read_b128 v[134:137], v0 offset:1024
	ds_read_b128 v[138:141], v0 offset:2048
	ds_read_b128 v[142:145], v0 offset:3072
	v_add_u32_e32 v0, s23, v247
	ds_read_b128 v[146:149], v0
	ds_read_b128 v[150:153], v0 offset:1024
	ds_read_b128 v[154:157], v0 offset:2048
	ds_read_b128 v[158:161], v0 offset:3072
	v_lshl_add_u64 v[210:211], s[0:1], 0, v[206:207]
	s_add_i32 m0, s67, 0xc000
	ds_read_b128 v[162:165], v249
	ds_read_b128 v[166:169], v249 offset:1024
	ds_read_b128 v[170:173], v249 offset:2048
	ds_read_b128 v[174:177], v249 offset:3072
	ds_read_b128 v[178:181], v249 offset:4096
	ds_read_b128 v[182:185], v249 offset:5120
	ds_read_b128 v[186:189], v249 offset:6144
	ds_read_b128 v[190:193], v249 offset:7168
	global_load_lds_dwordx4 v[210:211], off
	v_lshl_add_u64 v[210:211], s[0:1], 0, v[208:209]
	s_add_i32 m0, s67, 0xe000
	s_nop 0
	global_load_lds_dwordx4 v[210:211], off
	s_waitcnt vmcnt(8)
	s_waitcnt lgkmcnt(0)
	s_barrier
	s_setprio 1
	s_waitcnt lgkmcnt(0)
	v_mfma_f32_16x16x32_bf16 v[126:129], v[130:133], v[162:165], 0
	v_mfma_f32_16x16x32_bf16 v[118:121], v[138:141], v[162:165], 0
	v_mfma_f32_16x16x32_bf16 v[110:113], v[130:133], v[170:173], 0
	v_mfma_f32_16x16x32_bf16 v[102:105], v[138:141], v[170:173], 0
	v_mfma_f32_16x16x32_bf16 v[94:97], v[130:133], v[178:181], 0
	v_mfma_f32_16x16x32_bf16 v[86:89], v[138:141], v[178:181], 0
	v_mfma_f32_16x16x32_bf16 v[78:81], v[130:133], v[186:189], 0
	v_mfma_f32_16x16x32_bf16 v[70:73], v[138:141], v[186:189], 0
	v_mfma_f32_16x16x32_bf16 v[126:129], v[134:137], v[166:169], v[126:129]
	v_mfma_f32_16x16x32_bf16 v[118:121], v[142:145], v[166:169], v[118:121]
	v_mfma_f32_16x16x32_bf16 v[110:113], v[134:137], v[174:177], v[110:113]
	v_mfma_f32_16x16x32_bf16 v[102:105], v[142:145], v[174:177], v[102:105]
	v_mfma_f32_16x16x32_bf16 v[94:97], v[134:137], v[182:185], v[94:97]
	v_mfma_f32_16x16x32_bf16 v[86:89], v[142:145], v[182:185], v[86:89]
	v_mfma_f32_16x16x32_bf16 v[78:81], v[134:137], v[190:193], v[78:81]
	v_mfma_f32_16x16x32_bf16 v[70:73], v[142:145], v[190:193], v[70:73]
	s_setprio 0
	s_setprio 1
	v_mfma_f32_16x16x32_bf16 v[122:125], v[146:149], v[162:165], 0
	v_mfma_f32_16x16x32_bf16 v[114:117], v[154:157], v[162:165], 0
	v_mfma_f32_16x16x32_bf16 v[106:109], v[146:149], v[170:173], 0
	v_mfma_f32_16x16x32_bf16 v[98:101], v[154:157], v[170:173], 0
	v_mfma_f32_16x16x32_bf16 v[90:93], v[146:149], v[178:181], 0
	v_mfma_f32_16x16x32_bf16 v[82:85], v[154:157], v[178:181], 0
	v_mfma_f32_16x16x32_bf16 v[74:77], v[146:149], v[186:189], 0
	v_mfma_f32_16x16x32_bf16 v[66:69], v[154:157], v[186:189], 0
	v_mfma_f32_16x16x32_bf16 v[122:125], v[150:153], v[166:169], v[122:125]
	v_mfma_f32_16x16x32_bf16 v[114:117], v[158:161], v[166:169], v[114:117]
	v_mfma_f32_16x16x32_bf16 v[106:109], v[150:153], v[174:177], v[106:109]
	v_mfma_f32_16x16x32_bf16 v[98:101], v[158:161], v[174:177], v[98:101]
	v_mfma_f32_16x16x32_bf16 v[90:93], v[150:153], v[182:185], v[90:93]
	v_mfma_f32_16x16x32_bf16 v[82:85], v[158:161], v[182:185], v[82:85]
	v_mfma_f32_16x16x32_bf16 v[74:77], v[150:153], v[190:193], v[74:77]
	v_mfma_f32_16x16x32_bf16 v[66:69], v[158:161], v[190:193], v[66:69]
	s_setprio 0
	s_barrier
	s_add_i32 s49, s49, s2
	v_lshl_add_u64 v[210:211], s[50:51], 0, v[198:199]
	s_mov_b32 m0, s49
	ds_read_b128 v[162:165], v249 offset:16384
	ds_read_b128 v[166:169], v249 offset:17408
	ds_read_b128 v[170:173], v249 offset:18432
	ds_read_b128 v[174:177], v249 offset:19456
	ds_read_b128 v[178:181], v249 offset:20480
	ds_read_b128 v[182:185], v249 offset:21504
	ds_read_b128 v[186:189], v249 offset:22528
	ds_read_b128 v[190:193], v249 offset:23552
	global_load_lds_dwordx4 v[210:211], off
	s_add_i32 m0, s49, 0x2000
	v_lshl_add_u64 v[212:213], s[50:51], 0, v[202:203]
	s_add_u32 s50, s50, s74
	s_addc_u32 s51, s51, 0
	s_add_i32 s23, s23, s2
	global_load_lds_dwordx4 v[212:213], off
	v_lshl_add_u64 v[214:215], s[50:51], 0, v[198:199]
	s_mov_b32 m0, s23
	v_lshl_add_u64 v[216:217], s[50:51], 0, v[202:203]
	global_load_lds_dwordx4 v[214:215], off
	s_add_i32 m0, s23, 0x2000
	v_lshl_add_u64 v[218:219], s[38:39], 0, v[196:197]
	global_load_lds_dwordx4 v[216:217], off
	s_mov_b32 m0, s67
	v_lshl_add_u64 v[220:221], s[38:39], 0, v[200:201]
	global_load_lds_dwordx4 v[218:219], off
	s_mov_b32 m0, s7
	s_nop 0
	global_load_lds_dwordx4 v[220:221], off
	s_waitcnt vmcnt(8)
	s_waitcnt lgkmcnt(0)
	s_barrier
; #define PG8_STAGE(bufoff, gbase, voff) do { _Pragma("unroll") for (int _i = 0; _i < 2; ++_i) \
;         __builtin_amdgcn_global_load_lds((const unsigned*)((const char*)(gbase) + (voff)[_i]), (LAS unsigned*)(lds + (bufoff) + ldsw + _i * 8192), 16, 0, 0); } while (0)
; #define PG8_LDA(dst, b, h) do { _Pragma("unroll") for (int m = 0; m < 4; ++m) _Pragma("unroll") for (int k = 0; k < 2; ++k) dst[m][k] = *(const LAS bf16x8*)(lds + PG8_SA(b, h) + aoff + m * 2048 + k * 1024); } while (0)
; #define PG8_LDB(dst, b, h) do { _Pragma("unroll") for (int n = 0; n < 2; ++n) _Pragma("unroll") for (int k = 0; k < 2; ++k) dst[n][k] = *(const LAS bf16x8*)(lds + PG8_SB(b, h) + boff + n * 2048 + k * 1024); } while (0)
; #define PG8_MMA(ai, bj, At, Bt) do { __builtin_amdgcn_s_setprio(1); _Pragma("unroll") for (int m = 0; m < 4; ++m) _Pragma("unroll") for (int n = 0; n < 2; ++n) _Pragma("unroll") for (int k = 0; k < 2; ++k) \
;         acc[ai][bj][m][n] = __builtin_amdgcn_mfma_f32_16x16x32_bf16(Bt[n][k], At[m][k], acc[ai][bj][m][n], 0, 0, 0); __builtin_amdgcn_s_setprio(0); } while (0)
; #define PG8_WAIT_V(n) asm volatile("s_waitcnt vmcnt(" #n ")" ::: "memory")
; #define PG8_WAIT_L(n) asm volatile("s_waitcnt lgkmcnt(" #n ")" ::: "memory")
; #define PG8_BAR __builtin_amdgcn_s_barrier()
; #define PG8_SCHED __builtin_amdgcn_sched_barrier(0)
; __device__ __forceinline__ void gemm_phase(LAS unsigned char* lds, const Gemm g, const StaticOrder& S, const LAS Epi* Ep, const int tid) {
;     ...
;             PG8_WAIT_V(8); PG8_WAIT_L(0); PG8_BAR; PG8_MMA(1, 0, At, B0); PG8_MMA(1, 1, At, B1); PG8_BAR; PG8_SCHED;
;             PG8_LDB(B0, 1, 0); PG8_LDB(B1, 1, 1); PG8_SCHED; PG8_LDA(At, 1, 0); PG8_STAGE(PG8_SA(0, 1), a2 + hstepA, voffA);
;             PG8_WAIT_V(8); PG8_WAIT_L(0); PG8_BAR; PG8_MMA(0, 0, At, B0); PG8_MMA(0, 1, At, B1); PG8_BAR; PG8_SCHED;
	s_setprio 1
	s_waitcnt lgkmcnt(0)
	v_mfma_f32_16x16x32_bf16 v[62:65], v[130:133], v[162:165], 0
	v_mfma_f32_16x16x32_bf16 v[54:57], v[138:141], v[162:165], 0
	v_mfma_f32_16x16x32_bf16 v[46:49], v[130:133], v[170:173], 0
	v_mfma_f32_16x16x32_bf16 v[38:41], v[138:141], v[170:173], 0
	v_mfma_f32_16x16x32_bf16 v[30:33], v[130:133], v[178:181], 0
	v_mfma_f32_16x16x32_bf16 v[22:25], v[138:141], v[178:181], 0
	v_mfma_f32_16x16x32_bf16 v[14:17], v[130:133], v[186:189], 0
	v_mfma_f32_16x16x32_bf16 v[6:9], v[138:141], v[186:189], 0
	v_mfma_f32_16x16x32_bf16 v[62:65], v[134:137], v[166:169], v[62:65]
	v_mfma_f32_16x16x32_bf16 v[54:57], v[142:145], v[166:169], v[54:57]
	v_mfma_f32_16x16x32_bf16 v[46:49], v[134:137], v[174:177], v[46:49]
	v_mfma_f32_16x16x32_bf16 v[38:41], v[142:145], v[174:177], v[38:41]
	v_mfma_f32_16x16x32_bf16 v[30:33], v[134:137], v[182:185], v[30:33]
	v_mfma_f32_16x16x32_bf16 v[22:25], v[142:145], v[182:185], v[22:25]
	v_mfma_f32_16x16x32_bf16 v[14:17], v[134:137], v[190:193], v[14:17]
	v_mfma_f32_16x16x32_bf16 v[6:9], v[142:145], v[190:193], v[6:9]
	s_setprio 0
	s_setprio 1
	v_mfma_f32_16x16x32_bf16 v[58:61], v[146:149], v[162:165], 0
	v_mfma_f32_16x16x32_bf16 v[50:53], v[154:157], v[162:165], 0
	v_mfma_f32_16x16x32_bf16 v[42:45], v[146:149], v[170:173], 0
	v_mfma_f32_16x16x32_bf16 v[34:37], v[154:157], v[170:173], 0
	v_mfma_f32_16x16x32_bf16 v[26:29], v[146:149], v[178:181], 0
	v_mfma_f32_16x16x32_bf16 v[18:21], v[154:157], v[178:181], 0
	v_mfma_f32_16x16x32_bf16 v[10:13], v[146:149], v[186:189], 0
	v_mfma_f32_16x16x32_bf16 v[2:5], v[154:157], v[186:189], 0
	v_mfma_f32_16x16x32_bf16 v[58:61], v[150:153], v[166:169], v[58:61]
	v_mfma_f32_16x16x32_bf16 v[50:53], v[158:161], v[166:169], v[50:53]
	v_mfma_f32_16x16x32_bf16 v[42:45], v[150:153], v[174:177], v[42:45]
	v_mfma_f32_16x16x32_bf16 v[34:37], v[158:161], v[174:177], v[34:37]
	v_mfma_f32_16x16x32_bf16 v[26:29], v[150:153], v[182:185], v[26:29]
	v_mfma_f32_16x16x32_bf16 v[18:21], v[158:161], v[182:185], v[18:21]
	v_mfma_f32_16x16x32_bf16 v[10:13], v[150:153], v[190:193], v[10:13]
	v_mfma_f32_16x16x32_bf16 v[2:5], v[158:161], v[190:193], v[2:5]
	s_setprio 0
	s_barrier
	s_add_i32 s23, 0, 0x18000
	v_add_u32_e32 v0, s23, v247
	s_add_i32 s49, 0, 0x1c000
	ds_read_b128 v[130:133], v0
	ds_read_b128 v[134:137], v0 offset:1024
	ds_read_b128 v[138:141], v0 offset:2048
	ds_read_b128 v[142:145], v0 offset:3072
	v_add_u32_e32 v0, s49, v247
	ds_read_b128 v[146:149], v0
	ds_read_b128 v[150:153], v0 offset:1024
	ds_read_b128 v[154:157], v0 offset:2048
	ds_read_b128 v[158:161], v0 offset:3072
	s_add_u32 s38, s38, s86
	s_addc_u32 s39, s39, 0
	s_mov_b32 m0, s14
	v_lshl_add_u64 v[222:223], s[38:39], 0, v[196:197]
	ds_read_b128 v[162:165], v249 offset:32768
	ds_read_b128 v[166:169], v249 offset:33792
	ds_read_b128 v[170:173], v249 offset:34816
	ds_read_b128 v[174:177], v249 offset:35840
	ds_read_b128 v[178:181], v249 offset:36864
	ds_read_b128 v[182:185], v249 offset:37888
	ds_read_b128 v[186:189], v249 offset:38912
	ds_read_b128 v[190:193], v249 offset:39936
	global_load_lds_dwordx4 v[222:223], off
	v_lshl_add_u64 v[222:223], s[38:39], 0, v[200:201]
	s_mov_b32 m0, s15
	s_nop 0
	global_load_lds_dwordx4 v[222:223], off
	s_waitcnt vmcnt(8)
	s_waitcnt lgkmcnt(0)
	s_barrier
	s_setprio 1
	s_waitcnt lgkmcnt(0)
	v_mfma_f32_16x16x32_bf16 v[126:129], v[130:133], v[162:165], v[126:129]
	v_mfma_f32_16x16x32_bf16 v[118:121], v[138:141], v[162:165], v[118:121]
	v_mfma_f32_16x16x32_bf16 v[110:113], v[130:133], v[170:173], v[110:113]
	v_mfma_f32_16x16x32_bf16 v[102:105], v[138:141], v[170:173], v[102:105]
	v_mfma_f32_16x16x32_bf16 v[94:97], v[130:133], v[178:181], v[94:97]
	v_mfma_f32_16x16x32_bf16 v[86:89], v[138:141], v[178:181], v[86:89]
	v_mfma_f32_16x16x32_bf16 v[78:81], v[130:133], v[186:189], v[78:81]
	v_mfma_f32_16x16x32_bf16 v[70:73], v[138:141], v[186:189], v[70:73]
	v_mfma_f32_16x16x32_bf16 v[126:129], v[134:137], v[166:169], v[126:129]
	v_mfma_f32_16x16x32_bf16 v[118:121], v[142:145], v[166:169], v[118:121]
	v_mfma_f32_16x16x32_bf16 v[110:113], v[134:137], v[174:177], v[110:113]
	v_mfma_f32_16x16x32_bf16 v[102:105], v[142:145], v[174:177], v[102:105]
	v_mfma_f32_16x16x32_bf16 v[94:97], v[134:137], v[182:185], v[94:97]
	v_mfma_f32_16x16x32_bf16 v[86:89], v[142:145], v[182:185], v[86:89]
	v_mfma_f32_16x16x32_bf16 v[78:81], v[134:137], v[190:193], v[78:81]
	v_mfma_f32_16x16x32_bf16 v[70:73], v[142:145], v[190:193], v[70:73]
	s_setprio 0
	s_setprio 1
	v_mfma_f32_16x16x32_bf16 v[122:125], v[146:149], v[162:165], v[122:125]
	v_mfma_f32_16x16x32_bf16 v[114:117], v[154:157], v[162:165], v[114:117]
	v_mfma_f32_16x16x32_bf16 v[106:109], v[146:149], v[170:173], v[106:109]
	v_mfma_f32_16x16x32_bf16 v[98:101], v[154:157], v[170:173], v[98:101]
	v_mfma_f32_16x16x32_bf16 v[90:93], v[146:149], v[178:181], v[90:93]
	v_mfma_f32_16x16x32_bf16 v[82:85], v[154:157], v[178:181], v[82:85]
	v_mfma_f32_16x16x32_bf16 v[74:77], v[146:149], v[186:189], v[74:77]
	v_mfma_f32_16x16x32_bf16 v[66:69], v[154:157], v[186:189], v[66:69]
	v_mfma_f32_16x16x32_bf16 v[122:125], v[150:153], v[166:169], v[122:125]
	v_mfma_f32_16x16x32_bf16 v[114:117], v[158:161], v[166:169], v[114:117]
	v_mfma_f32_16x16x32_bf16 v[106:109], v[150:153], v[174:177], v[106:109]
	v_mfma_f32_16x16x32_bf16 v[98:101], v[158:161], v[174:177], v[98:101]
	v_mfma_f32_16x16x32_bf16 v[90:93], v[150:153], v[182:185], v[90:93]
	v_mfma_f32_16x16x32_bf16 v[82:85], v[158:161], v[182:185], v[82:85]
	v_mfma_f32_16x16x32_bf16 v[74:77], v[150:153], v[190:193], v[74:77]
	v_mfma_f32_16x16x32_bf16 v[66:69], v[158:161], v[190:193], v[66:69]
	s_setprio 0
	s_barrier
; #define PG8_STAGE(bufoff, gbase, voff) do { _Pragma("unroll") for (int _i = 0; _i < 2; ++_i) \
;         __builtin_amdgcn_global_load_lds((const unsigned*)((const char*)(gbase) + (voff)[_i]), (LAS unsigned*)(lds + (bufoff) + ldsw + _i * 8192), 16, 0, 0); } while (0)
; #define PG8_LDA(dst, b, h) do { _Pragma("unroll") for (int m = 0; m < 4; ++m) _Pragma("unroll") for (int k = 0; k < 2; ++k) dst[m][k] = *(const LAS bf16x8*)(lds + PG8_SA(b, h) + aoff + m * 2048 + k * 1024); } while (0)
; #define PG8_MMA(ai, bj, At, Bt) do { __builtin_amdgcn_s_setprio(1); _Pragma("unroll") for (int m = 0; m < 4; ++m) _Pragma("unroll") for (int n = 0; n < 2; ++n) _Pragma("unroll") for (int k = 0; k < 2; ++k) \
;         acc[ai][bj][m][n] = __builtin_amdgcn_mfma_f32_16x16x32_bf16(Bt[n][k], At[m][k], acc[ai][bj][m][n], 0, 0, 0); __builtin_amdgcn_s_setprio(0); } while (0)
; #define PG8_WAIT_V(n) asm volatile("s_waitcnt vmcnt(" #n ")" ::: "memory")
; #define PG8_WAIT_L(n) asm volatile("s_waitcnt lgkmcnt(" #n ")" ::: "memory")
; #define PG8_BAR __builtin_amdgcn_s_barrier()
; #define PG8_SCHED __builtin_amdgcn_sched_barrier(0)
; __device__ __forceinline__ void gemm_phase(LAS unsigned char* lds, const Gemm g, const StaticOrder& S, const LAS Epi* Ep, const int tid) {
;     ...
;             PG8_LDA(At, 1, 1); PG8_STAGE(PG8_SB(1, 0), b3, voffB); PG8_STAGE(PG8_SB(1, 1), b3 + hstepB, voffB); PG8_STAGE(PG8_SA(1, 0), a3, voffA);
;             PG8_WAIT_V(8); PG8_WAIT_L(0); PG8_BAR; PG8_MMA(1, 0, At, B0); PG8_MMA(1, 1, At, B1); PG8_BAR; PG8_SCHED;
;         }
	s_add_i32 s23, s23, s2
	v_lshl_add_u64 v[210:211], v[210:211], 0, s[88:89]
	s_mov_b32 m0, s23
	ds_read_b128 v[162:165], v249 offset:49152
	ds_read_b128 v[166:169], v249 offset:50176
	ds_read_b128 v[170:173], v249 offset:51200
	ds_read_b128 v[174:177], v249 offset:52224
	ds_read_b128 v[178:181], v249 offset:53248
	ds_read_b128 v[182:185], v249 offset:54272
	ds_read_b128 v[186:189], v249 offset:55296
	ds_read_b128 v[190:193], v249 offset:56320
	global_load_lds_dwordx4 v[210:211], off
	v_lshl_add_u64 v[210:211], v[212:213], 0, s[88:89]
	s_add_i32 m0, s23, 0x2000
	s_add_i32 s23, s49, s2
	global_load_lds_dwordx4 v[210:211], off
	v_lshl_add_u64 v[210:211], v[214:215], 0, s[88:89]
	s_mov_b32 m0, s23
	s_nop 0
	global_load_lds_dwordx4 v[210:211], off
	v_lshl_add_u64 v[210:211], v[216:217], 0, s[88:89]
	s_add_i32 m0, s23, 0x2000
	s_nop 0
	global_load_lds_dwordx4 v[210:211], off
	v_lshl_add_u64 v[210:211], v[218:219], 0, s[88:89]
	s_mov_b32 m0, s10
	s_nop 0
	global_load_lds_dwordx4 v[210:211], off
	v_lshl_add_u64 v[210:211], v[220:221], 0, s[88:89]
	s_mov_b32 m0, s11
	s_nop 0
	global_load_lds_dwordx4 v[210:211], off
	s_waitcnt vmcnt(8)
	s_waitcnt lgkmcnt(0)
	s_barrier
	s_setprio 1
	s_waitcnt lgkmcnt(0)
	v_mfma_f32_16x16x32_bf16 v[62:65], v[130:133], v[162:165], v[62:65]
	v_mfma_f32_16x16x32_bf16 v[54:57], v[138:141], v[162:165], v[54:57]
	v_mfma_f32_16x16x32_bf16 v[46:49], v[130:133], v[170:173], v[46:49]
	v_mfma_f32_16x16x32_bf16 v[38:41], v[138:141], v[170:173], v[38:41]
	v_mfma_f32_16x16x32_bf16 v[30:33], v[130:133], v[178:181], v[30:33]
	v_mfma_f32_16x16x32_bf16 v[22:25], v[138:141], v[178:181], v[22:25]
	v_mfma_f32_16x16x32_bf16 v[14:17], v[130:133], v[186:189], v[14:17]
	v_mfma_f32_16x16x32_bf16 v[6:9], v[138:141], v[186:189], v[6:9]
	v_mfma_f32_16x16x32_bf16 v[62:65], v[134:137], v[166:169], v[62:65]
	v_mfma_f32_16x16x32_bf16 v[54:57], v[142:145], v[166:169], v[54:57]
	v_mfma_f32_16x16x32_bf16 v[46:49], v[134:137], v[174:177], v[46:49]
	v_mfma_f32_16x16x32_bf16 v[38:41], v[142:145], v[174:177], v[38:41]
	v_mfma_f32_16x16x32_bf16 v[30:33], v[134:137], v[182:185], v[30:33]
	v_mfma_f32_16x16x32_bf16 v[22:25], v[142:145], v[182:185], v[22:25]
	v_mfma_f32_16x16x32_bf16 v[14:17], v[134:137], v[190:193], v[14:17]
	v_mfma_f32_16x16x32_bf16 v[6:9], v[142:145], v[190:193], v[6:9]
	s_setprio 0
	s_setprio 1
	v_mfma_f32_16x16x32_bf16 v[58:61], v[146:149], v[162:165], v[58:61]
	v_mfma_f32_16x16x32_bf16 v[50:53], v[154:157], v[162:165], v[50:53]
	v_mfma_f32_16x16x32_bf16 v[42:45], v[146:149], v[170:173], v[42:45]
	v_mfma_f32_16x16x32_bf16 v[34:37], v[154:157], v[170:173], v[34:37]
	v_mfma_f32_16x16x32_bf16 v[26:29], v[146:149], v[178:181], v[26:29]
	v_mfma_f32_16x16x32_bf16 v[18:21], v[154:157], v[178:181], v[18:21]
	v_mfma_f32_16x16x32_bf16 v[10:13], v[146:149], v[186:189], v[10:13]
	v_mfma_f32_16x16x32_bf16 v[2:5], v[154:157], v[186:189], v[2:5]
	v_mfma_f32_16x16x32_bf16 v[58:61], v[150:153], v[166:169], v[58:61]
	v_mfma_f32_16x16x32_bf16 v[50:53], v[158:161], v[166:169], v[50:53]
	v_mfma_f32_16x16x32_bf16 v[42:45], v[150:153], v[174:177], v[42:45]
	v_mfma_f32_16x16x32_bf16 v[34:37], v[158:161], v[174:177], v[34:37]
	v_mfma_f32_16x16x32_bf16 v[26:29], v[150:153], v[182:185], v[26:29]
	v_mfma_f32_16x16x32_bf16 v[18:21], v[158:161], v[182:185], v[18:21]
	v_mfma_f32_16x16x32_bf16 v[10:13], v[150:153], v[190:193], v[10:13]
	v_mfma_f32_16x16x32_bf16 v[2:5], v[158:161], v[190:193], v[2:5]
	s_setprio 0
	s_barrier
	s_add_u32 s0, s0, 0x100
	s_addc_u32 s1, s1, 0
	s_add_u32 s3, s3, 0x100
	s_addc_u32 s5, s5, 0
	s_cmp_ge_u32 s48, s16
	s_mov_b32 s23, s48
	s_cbranch_scc0 .LBB0_1434
	s_branch .Lpeel2_exit

; #define PG8_BAR __builtin_amdgcn_s_barrier()
; __device__ __forceinline__ void gemm_phase(LAS unsigned char* lds, const Gemm g, const StaticOrder& S, const LAS Epi* Ep, const int tid) {
;     ...
;         }
;         if (wr == 0) PG8_BAR;
.Lpeel2_exit:
	s_and_b64 vcc, exec, s[30:31]
	s_cbranch_vccz .LBB0_1437
	s_barrier

; #define PG8_STAGE(bufoff, gbase, voff) do { _Pragma("unroll") for (int _i = 0; _i < 2; ++_i) \
;         __builtin_amdgcn_global_load_lds((const unsigned*)((const char*)(gbase) + (voff)[_i]), (LAS unsigned*)(lds + (bufoff) + ldsw + _i * 8192), 16, 0, 0); } while (0)
; #define PG8_LDA(dst, b, h) do { _Pragma("unroll") for (int m = 0; m < 4; ++m) _Pragma("unroll") for (int k = 0; k < 2; ++k) dst[m][k] = *(const LAS bf16x8*)(lds + PG8_SA(b, h) + aoff + m * 2048 + k * 1024); } while (0)
; #define PG8_LDB(dst, b, h) do { _Pragma("unroll") for (int n = 0; n < 2; ++n) _Pragma("unroll") for (int k = 0; k < 2; ++k) dst[n][k] = *(const LAS bf16x8*)(lds + PG8_SB(b, h) + boff + n * 2048 + k * 1024); } while (0)
; #define PG8_MMA(ai, bj, At, Bt) do { __builtin_amdgcn_s_setprio(1); _Pragma("unroll") for (int m = 0; m < 4; ++m) _Pragma("unroll") for (int n = 0; n < 2; ++n) _Pragma("unroll") for (int k = 0; k < 2; ++k) \
;         acc[ai][bj][m][n] = __builtin_amdgcn_mfma_f32_16x16x32_bf16(Bt[n][k], At[m][k], acc[ai][bj][m][n], 0, 0, 0); __builtin_amdgcn_s_setprio(0); } while (0)
; #define PG8_WAIT_V(n) asm volatile("s_waitcnt vmcnt(" #n ")" ::: "memory")
; #define PG8_WAIT_L(n) asm volatile("s_waitcnt lgkmcnt(" #n ")" ::: "memory")
; #define PG8_BAR __builtin_amdgcn_s_barrier()
; #define PG8_SCHED __builtin_amdgcn_sched_barrier(0)
; __device__ __forceinline__ void gemm_phase(LAS unsigned char* lds, const Gemm g, const StaticOrder& S, const LAS Epi* Ep, const int tid) {
;     ...
;         for (int t = 0; t < nt; t += 2) {
;             const bool last = (t == nt - 2);
;             const char* a1 = cA + (size_t)(t + 1) * kstep;
;             const char* a2 = last ? nA : cA + (size_t)(t + 2) * kstep; const char* b2 = last ? nB : cB + (size_t)(t + 2) * kstep;
;             const char* a3 = a2 + kstep; const char* b3 = b2 + kstep;
;             PG8_LDB(B0, 0, 0); PG8_LDB(B1, 0, 1); PG8_SCHED; PG8_LDA(At, 0, 0); PG8_STAGE(PG8_SA(1, 1), a1 + hstepA, voffA);
;             PG8_WAIT_V(8); PG8_WAIT_L(0); PG8_BAR; PG8_MMA(0, 0, At, B0); PG8_MMA(0, 1, At, B1); PG8_BAR; PG8_SCHED;
;             PG8_LDA(At, 0, 1); PG8_STAGE(PG8_SB(0, 0), b2, voffB); PG8_STAGE(PG8_SB(0, 1), b2 + hstepB, voffB); PG8_STAGE(PG8_SA(0, 0), a2, voffA);
.LBB0_1845:
	s_add_u32 s0, s0, 0x80
	s_addc_u32 s1, s1, 0
	s_add_u32 s3, s10, 0x100
	s_addc_u32 s12, s11, 0
	s_mov_b32 s10, 0
	s_waitcnt vmcnt(0)
	s_add_i32 s13, s10, 2
	s_add_u32 s14, s0, 0x80
	s_addc_u32 s11, s1, 0
	s_add_i32 s16, 0, 0x10000
	s_cmp_eq_u32 s68, s10
	s_cselect_b32 s11, s7, s11
	s_cselect_b32 s10, s6, s14
	v_add_u32_e32 v2, s16, v230
	s_cselect_b32 s15, s9, s12
	s_cselect_b32 s14, s8, s3
	s_add_i32 s17, 0, 0x14000
	s_waitcnt lgkmcnt(0)
	ds_read_b128 v[132:135], v2
	ds_read_b128 v[136:139], v2 offset:1024
	ds_read_b128 v[140:143], v2 offset:2048
	ds_read_b128 v[144:147], v2 offset:3072
	v_add_u32_e32 v2, s17, v230
	ds_read_b128 v[148:151], v2
	ds_read_b128 v[152:155], v2 offset:1024
	ds_read_b128 v[156:159], v2 offset:2048
	ds_read_b128 v[160:163], v2 offset:3072
	v_lshl_add_u64 v[210:211], s[0:1], 0, v[206:207]
	s_add_i32 m0, s87, 0xc000
	ds_read_b128 v[164:167], v232
	ds_read_b128 v[168:171], v232 offset:1024
	ds_read_b128 v[172:175], v232 offset:2048
	ds_read_b128 v[176:179], v232 offset:3072
	ds_read_b128 v[180:183], v232 offset:4096
	ds_read_b128 v[184:187], v232 offset:5120
	ds_read_b128 v[188:191], v232 offset:6144
	ds_read_b128 v[192:195], v232 offset:7168
	global_load_lds_dwordx4 v[210:211], off
	v_lshl_add_u64 v[210:211], s[0:1], 0, v[208:209]
	s_add_i32 m0, s87, 0xe000
	s_nop 0
	global_load_lds_dwordx4 v[210:211], off
	s_waitcnt vmcnt(8)
	s_waitcnt lgkmcnt(0)
	s_barrier
	s_setprio 1
	s_waitcnt lgkmcnt(0)
	v_mfma_f32_16x16x32_bf16 v[128:131], v[132:135], v[164:167], 0
	v_mfma_f32_16x16x32_bf16 v[120:123], v[140:143], v[164:167], 0
	v_mfma_f32_16x16x32_bf16 v[112:115], v[132:135], v[172:175], 0
	v_mfma_f32_16x16x32_bf16 v[104:107], v[140:143], v[172:175], 0
	v_mfma_f32_16x16x32_bf16 v[96:99], v[132:135], v[180:183], 0
	v_mfma_f32_16x16x32_bf16 v[88:91], v[140:143], v[180:183], 0
	v_mfma_f32_16x16x32_bf16 v[80:83], v[132:135], v[188:191], 0
	v_mfma_f32_16x16x32_bf16 v[72:75], v[140:143], v[188:191], 0
	v_mfma_f32_16x16x32_bf16 v[128:131], v[136:139], v[168:171], v[128:131]
	v_mfma_f32_16x16x32_bf16 v[120:123], v[144:147], v[168:171], v[120:123]
	v_mfma_f32_16x16x32_bf16 v[112:115], v[136:139], v[176:179], v[112:115]
	v_mfma_f32_16x16x32_bf16 v[104:107], v[144:147], v[176:179], v[104:107]
	v_mfma_f32_16x16x32_bf16 v[96:99], v[136:139], v[184:187], v[96:99]
	v_mfma_f32_16x16x32_bf16 v[88:91], v[144:147], v[184:187], v[88:91]
	v_mfma_f32_16x16x32_bf16 v[80:83], v[136:139], v[192:195], v[80:83]
	v_mfma_f32_16x16x32_bf16 v[72:75], v[144:147], v[192:195], v[72:75]
	s_setprio 0
	s_setprio 1
	v_mfma_f32_16x16x32_bf16 v[124:127], v[148:151], v[164:167], 0
	v_mfma_f32_16x16x32_bf16 v[116:119], v[156:159], v[164:167], 0
	v_mfma_f32_16x16x32_bf16 v[108:111], v[148:151], v[172:175], 0
	v_mfma_f32_16x16x32_bf16 v[100:103], v[156:159], v[172:175], 0
	v_mfma_f32_16x16x32_bf16 v[92:95], v[148:151], v[180:183], 0
	v_mfma_f32_16x16x32_bf16 v[84:87], v[156:159], v[180:183], 0
	v_mfma_f32_16x16x32_bf16 v[76:79], v[148:151], v[188:191], 0
	v_mfma_f32_16x16x32_bf16 v[68:71], v[156:159], v[188:191], 0
	v_mfma_f32_16x16x32_bf16 v[124:127], v[152:155], v[168:171], v[124:127]
	v_mfma_f32_16x16x32_bf16 v[116:119], v[160:163], v[168:171], v[116:119]
	v_mfma_f32_16x16x32_bf16 v[108:111], v[152:155], v[176:179], v[108:111]
	v_mfma_f32_16x16x32_bf16 v[100:103], v[160:163], v[176:179], v[100:103]
	v_mfma_f32_16x16x32_bf16 v[92:95], v[152:155], v[184:187], v[92:95]
	v_mfma_f32_16x16x32_bf16 v[84:87], v[160:163], v[184:187], v[84:87]
	v_mfma_f32_16x16x32_bf16 v[76:79], v[152:155], v[192:195], v[76:79]
	v_mfma_f32_16x16x32_bf16 v[68:71], v[160:163], v[192:195], v[68:71]
	s_setprio 0
	s_barrier
	s_add_i32 s16, s16, s86
	v_lshl_add_u64 v[210:211], s[14:15], 0, v[196:197]
	s_mov_b32 m0, s16
	ds_read_b128 v[164:167], v232 offset:16384
	ds_read_b128 v[168:171], v232 offset:17408
	ds_read_b128 v[172:175], v232 offset:18432
	ds_read_b128 v[176:179], v232 offset:19456
	ds_read_b128 v[180:183], v232 offset:20480
	ds_read_b128 v[184:187], v232 offset:21504
	ds_read_b128 v[188:191], v232 offset:22528
	ds_read_b128 v[192:195], v232 offset:23552
	global_load_lds_dwordx4 v[210:211], off
	s_add_i32 m0, s16, 0x2000
	v_lshl_add_u64 v[212:213], s[14:15], 0, v[200:201]
	s_add_u32 s14, s14, s58
	s_addc_u32 s15, s15, 0
	s_add_i32 s16, s17, s86
	global_load_lds_dwordx4 v[212:213], off
	v_lshl_add_u64 v[214:215], s[14:15], 0, v[196:197]
	s_mov_b32 m0, s16
	v_lshl_add_u64 v[216:217], s[14:15], 0, v[200:201]
	global_load_lds_dwordx4 v[214:215], off
	s_add_i32 m0, s16, 0x2000
	v_lshl_add_u64 v[218:219], s[10:11], 0, v[0:1]
	global_load_lds_dwordx4 v[216:217], off
	s_mov_b32 m0, s87
	v_lshl_add_u64 v[220:221], s[10:11], 0, v[198:199]
	global_load_lds_dwordx4 v[218:219], off
	s_mov_b32 m0, s38
	s_nop 0
	global_load_lds_dwordx4 v[220:221], off
	s_waitcnt vmcnt(8)
	s_waitcnt lgkmcnt(0)
	s_barrier
; #define PG8_STAGE(bufoff, gbase, voff) do { _Pragma("unroll") for (int _i = 0; _i < 2; ++_i) \
;         __builtin_amdgcn_global_load_lds((const unsigned*)((const char*)(gbase) + (voff)[_i]), (LAS unsigned*)(lds + (bufoff) + ldsw + _i * 8192), 16, 0, 0); } while (0)
; #define PG8_LDA(dst, b, h) do { _Pragma("unroll") for (int m = 0; m < 4; ++m) _Pragma("unroll") for (int k = 0; k < 2; ++k) dst[m][k] = *(const LAS bf16x8*)(lds + PG8_SA(b, h) + aoff + m * 2048 + k * 1024); } while (0)
; #define PG8_LDB(dst, b, h) do { _Pragma("unroll") for (int n = 0; n < 2; ++n) _Pragma("unroll") for (int k = 0; k < 2; ++k) dst[n][k] = *(const LAS bf16x8*)(lds + PG8_SB(b, h) + boff + n * 2048 + k * 1024); } while (0)
; #define PG8_MMA(ai, bj, At, Bt) do { __builtin_amdgcn_s_setprio(1); _Pragma("unroll") for (int m = 0; m < 4; ++m) _Pragma("unroll") for (int n = 0; n < 2; ++n) _Pragma("unroll") for (int k = 0; k < 2; ++k) \
;         acc[ai][bj][m][n] = __builtin_amdgcn_mfma_f32_16x16x32_bf16(Bt[n][k], At[m][k], acc[ai][bj][m][n], 0, 0, 0); __builtin_amdgcn_s_setprio(0); } while (0)
; #define PG8_WAIT_V(n) asm volatile("s_waitcnt vmcnt(" #n ")" ::: "memory")
; #define PG8_WAIT_L(n) asm volatile("s_waitcnt lgkmcnt(" #n ")" ::: "memory")
; #define PG8_BAR __builtin_amdgcn_s_barrier()
; #define PG8_SCHED __builtin_amdgcn_sched_barrier(0)
; __device__ __forceinline__ void gemm_phase(LAS unsigned char* lds, const Gemm g, const StaticOrder& S, const LAS Epi* Ep, const int tid) {
;     ...
;             PG8_WAIT_V(8); PG8_WAIT_L(0); PG8_BAR; PG8_MMA(1, 0, At, B0); PG8_MMA(1, 1, At, B1); PG8_BAR; PG8_SCHED;
;             PG8_LDB(B0, 1, 0); PG8_LDB(B1, 1, 1); PG8_SCHED; PG8_LDA(At, 1, 0); PG8_STAGE(PG8_SA(0, 1), a2 + hstepA, voffA);
;             PG8_WAIT_V(8); PG8_WAIT_L(0); PG8_BAR; PG8_MMA(0, 0, At, B0); PG8_MMA(0, 1, At, B1); PG8_BAR; PG8_SCHED;
	s_setprio 1
	s_waitcnt lgkmcnt(0)
	v_mfma_f32_16x16x32_bf16 v[64:67], v[132:135], v[164:167], 0
	v_mfma_f32_16x16x32_bf16 v[56:59], v[140:143], v[164:167], 0
	v_mfma_f32_16x16x32_bf16 v[48:51], v[132:135], v[172:175], 0
	v_mfma_f32_16x16x32_bf16 v[40:43], v[140:143], v[172:175], 0
	v_mfma_f32_16x16x32_bf16 v[32:35], v[132:135], v[180:183], 0
	v_mfma_f32_16x16x32_bf16 v[24:27], v[140:143], v[180:183], 0
	v_mfma_f32_16x16x32_bf16 v[16:19], v[132:135], v[188:191], 0
	v_mfma_f32_16x16x32_bf16 v[8:11], v[140:143], v[188:191], 0
	v_mfma_f32_16x16x32_bf16 v[64:67], v[136:139], v[168:171], v[64:67]
	v_mfma_f32_16x16x32_bf16 v[56:59], v[144:147], v[168:171], v[56:59]
	v_mfma_f32_16x16x32_bf16 v[48:51], v[136:139], v[176:179], v[48:51]
	v_mfma_f32_16x16x32_bf16 v[40:43], v[144:147], v[176:179], v[40:43]
	v_mfma_f32_16x16x32_bf16 v[32:35], v[136:139], v[184:187], v[32:35]
	v_mfma_f32_16x16x32_bf16 v[24:27], v[144:147], v[184:187], v[24:27]
	v_mfma_f32_16x16x32_bf16 v[16:19], v[136:139], v[192:195], v[16:19]
	v_mfma_f32_16x16x32_bf16 v[8:11], v[144:147], v[192:195], v[8:11]
	s_setprio 0
	s_setprio 1
	v_mfma_f32_16x16x32_bf16 v[60:63], v[148:151], v[164:167], 0
	v_mfma_f32_16x16x32_bf16 v[52:55], v[156:159], v[164:167], 0
	v_mfma_f32_16x16x32_bf16 v[44:47], v[148:151], v[172:175], 0
	v_mfma_f32_16x16x32_bf16 v[36:39], v[156:159], v[172:175], 0
	v_mfma_f32_16x16x32_bf16 v[28:31], v[148:151], v[180:183], 0
	v_mfma_f32_16x16x32_bf16 v[20:23], v[156:159], v[180:183], 0
	v_mfma_f32_16x16x32_bf16 v[12:15], v[148:151], v[188:191], 0
	v_mfma_f32_16x16x32_bf16 v[4:7], v[156:159], v[188:191], 0
	v_mfma_f32_16x16x32_bf16 v[60:63], v[152:155], v[168:171], v[60:63]
	v_mfma_f32_16x16x32_bf16 v[52:55], v[160:163], v[168:171], v[52:55]
	v_mfma_f32_16x16x32_bf16 v[44:47], v[152:155], v[176:179], v[44:47]
	v_mfma_f32_16x16x32_bf16 v[36:39], v[160:163], v[176:179], v[36:39]
	v_mfma_f32_16x16x32_bf16 v[28:31], v[152:155], v[184:187], v[28:31]
	v_mfma_f32_16x16x32_bf16 v[20:23], v[160:163], v[184:187], v[20:23]
	v_mfma_f32_16x16x32_bf16 v[12:15], v[152:155], v[192:195], v[12:15]
	v_mfma_f32_16x16x32_bf16 v[4:7], v[160:163], v[192:195], v[4:7]
	s_setprio 0
	s_barrier
	s_add_i32 s14, 0, 0x18000
	v_add_u32_e32 v2, s14, v230
	s_add_i32 s15, 0, 0x1c000
	ds_read_b128 v[132:135], v2
	ds_read_b128 v[136:139], v2 offset:1024
	ds_read_b128 v[140:143], v2 offset:2048
	ds_read_b128 v[144:147], v2 offset:3072
	v_add_u32_e32 v2, s15, v230
	ds_read_b128 v[148:151], v2
	ds_read_b128 v[152:155], v2 offset:1024
	ds_read_b128 v[156:159], v2 offset:2048
	ds_read_b128 v[160:163], v2 offset:3072
	s_add_u32 s10, s10, s58
	s_addc_u32 s11, s11, 0
	s_mov_b32 m0, s39
	v_lshl_add_u64 v[222:223], s[10:11], 0, v[0:1]
	ds_read_b128 v[164:167], v232 offset:32768
	ds_read_b128 v[168:171], v232 offset:33792
	ds_read_b128 v[172:175], v232 offset:34816
	ds_read_b128 v[176:179], v232 offset:35840
	ds_read_b128 v[180:183], v232 offset:36864
	ds_read_b128 v[184:187], v232 offset:37888
	ds_read_b128 v[188:191], v232 offset:38912
	ds_read_b128 v[192:195], v232 offset:39936
	global_load_lds_dwordx4 v[222:223], off
	v_lshl_add_u64 v[222:223], s[10:11], 0, v[198:199]
	s_mov_b32 m0, s88
	s_nop 0
	global_load_lds_dwordx4 v[222:223], off
	s_waitcnt vmcnt(8)
	s_waitcnt lgkmcnt(0)
	s_barrier
	s_setprio 1
	s_waitcnt lgkmcnt(0)
	v_mfma_f32_16x16x32_bf16 v[128:131], v[132:135], v[164:167], v[128:131]
	v_mfma_f32_16x16x32_bf16 v[120:123], v[140:143], v[164:167], v[120:123]
	v_mfma_f32_16x16x32_bf16 v[112:115], v[132:135], v[172:175], v[112:115]
	v_mfma_f32_16x16x32_bf16 v[104:107], v[140:143], v[172:175], v[104:107]
	v_mfma_f32_16x16x32_bf16 v[96:99], v[132:135], v[180:183], v[96:99]
	v_mfma_f32_16x16x32_bf16 v[88:91], v[140:143], v[180:183], v[88:91]
	v_mfma_f32_16x16x32_bf16 v[80:83], v[132:135], v[188:191], v[80:83]
	v_mfma_f32_16x16x32_bf16 v[72:75], v[140:143], v[188:191], v[72:75]
	v_mfma_f32_16x16x32_bf16 v[128:131], v[136:139], v[168:171], v[128:131]
	v_mfma_f32_16x16x32_bf16 v[120:123], v[144:147], v[168:171], v[120:123]
	v_mfma_f32_16x16x32_bf16 v[112:115], v[136:139], v[176:179], v[112:115]
	v_mfma_f32_16x16x32_bf16 v[104:107], v[144:147], v[176:179], v[104:107]
	v_mfma_f32_16x16x32_bf16 v[96:99], v[136:139], v[184:187], v[96:99]
	v_mfma_f32_16x16x32_bf16 v[88:91], v[144:147], v[184:187], v[88:91]
	v_mfma_f32_16x16x32_bf16 v[80:83], v[136:139], v[192:195], v[80:83]
	v_mfma_f32_16x16x32_bf16 v[72:75], v[144:147], v[192:195], v[72:75]
	s_setprio 0
	s_setprio 1
	v_mfma_f32_16x16x32_bf16 v[124:127], v[148:151], v[164:167], v[124:127]
	v_mfma_f32_16x16x32_bf16 v[116:119], v[156:159], v[164:167], v[116:119]
	v_mfma_f32_16x16x32_bf16 v[108:111], v[148:151], v[172:175], v[108:111]
	v_mfma_f32_16x16x32_bf16 v[100:103], v[156:159], v[172:175], v[100:103]
	v_mfma_f32_16x16x32_bf16 v[92:95], v[148:151], v[180:183], v[92:95]
	v_mfma_f32_16x16x32_bf16 v[84:87], v[156:159], v[180:183], v[84:87]
	v_mfma_f32_16x16x32_bf16 v[76:79], v[148:151], v[188:191], v[76:79]
	v_mfma_f32_16x16x32_bf16 v[68:71], v[156:159], v[188:191], v[68:71]
	v_mfma_f32_16x16x32_bf16 v[124:127], v[152:155], v[168:171], v[124:127]
	v_mfma_f32_16x16x32_bf16 v[116:119], v[160:163], v[168:171], v[116:119]
	v_mfma_f32_16x16x32_bf16 v[108:111], v[152:155], v[176:179], v[108:111]
	v_mfma_f32_16x16x32_bf16 v[100:103], v[160:163], v[176:179], v[100:103]
	v_mfma_f32_16x16x32_bf16 v[92:95], v[152:155], v[184:187], v[92:95]
	v_mfma_f32_16x16x32_bf16 v[84:87], v[160:163], v[184:187], v[84:87]
	v_mfma_f32_16x16x32_bf16 v[76:79], v[152:155], v[192:195], v[76:79]
	v_mfma_f32_16x16x32_bf16 v[68:71], v[160:163], v[192:195], v[68:71]
	s_setprio 0
	s_barrier
; #define PG8_STAGE(bufoff, gbase, voff) do { _Pragma("unroll") for (int _i = 0; _i < 2; ++_i) \
;         __builtin_amdgcn_global_load_lds((const unsigned*)((const char*)(gbase) + (voff)[_i]), (LAS unsigned*)(lds + (bufoff) + ldsw + _i * 8192), 16, 0, 0); } while (0)
; #define PG8_LDA(dst, b, h) do { _Pragma("unroll") for (int m = 0; m < 4; ++m) _Pragma("unroll") for (int k = 0; k < 2; ++k) dst[m][k] = *(const LAS bf16x8*)(lds + PG8_SA(b, h) + aoff + m * 2048 + k * 1024); } while (0)
; #define PG8_LDB(dst, b, h) do { _Pragma("unroll") for (int n = 0; n < 2; ++n) _Pragma("unroll") for (int k = 0; k < 2; ++k) dst[n][k] = *(const LAS bf16x8*)(lds + PG8_SB(b, h) + boff + n * 2048 + k * 1024); } while (0)
; #define PG8_MMA(ai, bj, At, Bt) do { __builtin_amdgcn_s_setprio(1); _Pragma("unroll") for (int m = 0; m < 4; ++m) _Pragma("unroll") for (int n = 0; n < 2; ++n) _Pragma("unroll") for (int k = 0; k < 2; ++k) \
;         acc[ai][bj][m][n] = __builtin_amdgcn_mfma_f32_16x16x32_bf16(Bt[n][k], At[m][k], acc[ai][bj][m][n], 0, 0, 0); __builtin_amdgcn_s_setprio(0); } while (0)
; #define PG8_WAIT_V(n) asm volatile("s_waitcnt vmcnt(" #n ")" ::: "memory")
; #define PG8_WAIT_L(n) asm volatile("s_waitcnt lgkmcnt(" #n ")" ::: "memory")
; #define PG8_BAR __builtin_amdgcn_s_barrier()
; #define PG8_SCHED __builtin_amdgcn_sched_barrier(0)
; __device__ __forceinline__ void gemm_phase(LAS unsigned char* lds, const Gemm g, const StaticOrder& S, const LAS Epi* Ep, const int tid) {
;     ...
;         for (int t = 0; t < nt; t += 2) {
;             const bool last = (t == nt - 2);
;             const char* a1 = cA + (size_t)(t + 1) * kstep;
;             const char* a2 = last ? nA : cA + (size_t)(t + 2) * kstep; const char* b2 = last ? nB : cB + (size_t)(t + 2) * kstep;
;             const char* a3 = a2 + kstep; const char* b3 = b2 + kstep;
;             PG8_LDB(B0, 0, 0); PG8_LDB(B1, 0, 1); PG8_SCHED; PG8_LDA(At, 0, 0); PG8_STAGE(PG8_SA(1, 1), a1 + hstepA, voffA);
;             PG8_WAIT_V(8); PG8_WAIT_L(0); PG8_BAR; PG8_MMA(0, 0, At, B0); PG8_MMA(0, 1, At, B1); PG8_BAR; PG8_SCHED;
;     ...
;             PG8_LDA(At, 1, 1); PG8_STAGE(PG8_SB(1, 0), b3, voffB); PG8_STAGE(PG8_SB(1, 1), b3 + hstepB, voffB); PG8_STAGE(PG8_SA(1, 0), a3, voffA);
;             PG8_WAIT_V(8); PG8_WAIT_L(0); PG8_BAR; PG8_MMA(1, 0, At, B0); PG8_MMA(1, 1, At, B1); PG8_BAR; PG8_SCHED;
;         }
	s_add_i32 s10, s14, s86
	v_lshl_add_u64 v[210:211], v[210:211], 0, s[90:91]
	s_mov_b32 m0, s10
	ds_read_b128 v[164:167], v232 offset:49152
	ds_read_b128 v[168:171], v232 offset:50176
	ds_read_b128 v[172:175], v232 offset:51200
	ds_read_b128 v[176:179], v232 offset:52224
	ds_read_b128 v[180:183], v232 offset:53248
	ds_read_b128 v[184:187], v232 offset:54272
	ds_read_b128 v[188:191], v232 offset:55296
	ds_read_b128 v[192:195], v232 offset:56320
	global_load_lds_dwordx4 v[210:211], off
	v_lshl_add_u64 v[210:211], v[212:213], 0, s[90:91]
	s_add_i32 m0, s10, 0x2000
	s_add_i32 s10, s15, s86
	global_load_lds_dwordx4 v[210:211], off
	v_lshl_add_u64 v[210:211], v[214:215], 0, s[90:91]
	s_mov_b32 m0, s10
	s_nop 0
	global_load_lds_dwordx4 v[210:211], off
	v_lshl_add_u64 v[210:211], v[216:217], 0, s[90:91]
	s_add_i32 m0, s10, 0x2000
	s_nop 0
	global_load_lds_dwordx4 v[210:211], off
	v_lshl_add_u64 v[210:211], v[218:219], 0, s[90:91]
	s_mov_b32 m0, s89
	s_nop 0
	global_load_lds_dwordx4 v[210:211], off
	v_lshl_add_u64 v[210:211], v[220:221], 0, s[90:91]
	s_mov_b32 m0, s36
	s_nop 0
	global_load_lds_dwordx4 v[210:211], off
	s_waitcnt vmcnt(8)
	s_waitcnt lgkmcnt(0)
	s_barrier
	s_setprio 1
	s_waitcnt lgkmcnt(0)
	v_mfma_f32_16x16x32_bf16 v[64:67], v[132:135], v[164:167], v[64:67]
	v_mfma_f32_16x16x32_bf16 v[56:59], v[140:143], v[164:167], v[56:59]
	v_mfma_f32_16x16x32_bf16 v[48:51], v[132:135], v[172:175], v[48:51]
	v_mfma_f32_16x16x32_bf16 v[40:43], v[140:143], v[172:175], v[40:43]
	v_mfma_f32_16x16x32_bf16 v[32:35], v[132:135], v[180:183], v[32:35]
	v_mfma_f32_16x16x32_bf16 v[24:27], v[140:143], v[180:183], v[24:27]
	v_mfma_f32_16x16x32_bf16 v[16:19], v[132:135], v[188:191], v[16:19]
	v_mfma_f32_16x16x32_bf16 v[8:11], v[140:143], v[188:191], v[8:11]
	v_mfma_f32_16x16x32_bf16 v[64:67], v[136:139], v[168:171], v[64:67]
	v_mfma_f32_16x16x32_bf16 v[56:59], v[144:147], v[168:171], v[56:59]
	v_mfma_f32_16x16x32_bf16 v[48:51], v[136:139], v[176:179], v[48:51]
	v_mfma_f32_16x16x32_bf16 v[40:43], v[144:147], v[176:179], v[40:43]
	v_mfma_f32_16x16x32_bf16 v[32:35], v[136:139], v[184:187], v[32:35]
	v_mfma_f32_16x16x32_bf16 v[24:27], v[144:147], v[184:187], v[24:27]
	v_mfma_f32_16x16x32_bf16 v[16:19], v[136:139], v[192:195], v[16:19]
	v_mfma_f32_16x16x32_bf16 v[8:11], v[144:147], v[192:195], v[8:11]
	s_setprio 0
	s_setprio 1
	v_mfma_f32_16x16x32_bf16 v[60:63], v[148:151], v[164:167], v[60:63]
	v_mfma_f32_16x16x32_bf16 v[52:55], v[156:159], v[164:167], v[52:55]
	v_mfma_f32_16x16x32_bf16 v[44:47], v[148:151], v[172:175], v[44:47]
	v_mfma_f32_16x16x32_bf16 v[36:39], v[156:159], v[172:175], v[36:39]
	v_mfma_f32_16x16x32_bf16 v[28:31], v[148:151], v[180:183], v[28:31]
	v_mfma_f32_16x16x32_bf16 v[20:23], v[156:159], v[180:183], v[20:23]
	v_mfma_f32_16x16x32_bf16 v[12:15], v[148:151], v[188:191], v[12:15]
	v_mfma_f32_16x16x32_bf16 v[4:7], v[156:159], v[188:191], v[4:7]
	v_mfma_f32_16x16x32_bf16 v[60:63], v[152:155], v[168:171], v[60:63]
	v_mfma_f32_16x16x32_bf16 v[52:55], v[160:163], v[168:171], v[52:55]
	v_mfma_f32_16x16x32_bf16 v[44:47], v[152:155], v[176:179], v[44:47]
	v_mfma_f32_16x16x32_bf16 v[36:39], v[160:163], v[176:179], v[36:39]
	v_mfma_f32_16x16x32_bf16 v[28:31], v[152:155], v[184:187], v[28:31]
	v_mfma_f32_16x16x32_bf16 v[20:23], v[160:163], v[184:187], v[20:23]
	v_mfma_f32_16x16x32_bf16 v[12:15], v[152:155], v[192:195], v[12:15]
	v_mfma_f32_16x16x32_bf16 v[4:7], v[160:163], v[192:195], v[4:7]
	s_setprio 0
	s_barrier
	s_add_u32 s0, s0, 0x100
	s_addc_u32 s1, s1, 0
	s_add_u32 s3, s3, 0x100
	s_addc_u32 s12, s12, 0
	s_cmp_ge_u32 s13, s70
	s_mov_b32 s10, s13
	s_cbranch_scc0 .LBB0_1846
	s_branch .Lpeel3_exit
.LBB0_1846:
	s_add_i32 s13, s10, 2
	s_add_u32 s14, s0, 0x80
	s_addc_u32 s11, s1, 0
	s_add_i32 s16, 0, 0x10000
	s_cmp_eq_u32 s68, s10
	s_cselect_b32 s11, s7, s11
	s_cselect_b32 s10, s6, s14
	v_add_u32_e32 v2, s16, v230
	s_cselect_b32 s15, s9, s12
	s_cselect_b32 s14, s8, s3
	s_add_i32 s17, 0, 0x14000
	s_waitcnt lgkmcnt(0)
	ds_read_b128 v[132:135], v2
	ds_read_b128 v[136:139], v2 offset:1024
	ds_read_b128 v[140:143], v2 offset:2048
	ds_read_b128 v[144:147], v2 offset:3072
	v_add_u32_e32 v2, s17, v230
	ds_read_b128 v[148:151], v2
	ds_read_b128 v[152:155], v2 offset:1024
	ds_read_b128 v[156:159], v2 offset:2048
	ds_read_b128 v[160:163], v2 offset:3072
	v_lshl_add_u64 v[210:211], s[0:1], 0, v[206:207]
	s_add_i32 m0, s87, 0xc000
	ds_read_b128 v[164:167], v232
	ds_read_b128 v[168:171], v232 offset:1024
	ds_read_b128 v[172:175], v232 offset:2048
	ds_read_b128 v[176:179], v232 offset:3072
	ds_read_b128 v[180:183], v232 offset:4096
	ds_read_b128 v[184:187], v232 offset:5120
	ds_read_b128 v[188:191], v232 offset:6144
	ds_read_b128 v[192:195], v232 offset:7168
	global_load_lds_dwordx4 v[210:211], off
	v_lshl_add_u64 v[210:211], s[0:1], 0, v[208:209]
	s_add_i32 m0, s87, 0xe000
	s_nop 0
	global_load_lds_dwordx4 v[210:211], off
	s_waitcnt vmcnt(8)
	s_waitcnt lgkmcnt(0)
	s_barrier
; #define PG8_STAGE(bufoff, gbase, voff) do { _Pragma("unroll") for (int _i = 0; _i < 2; ++_i) \
;         __builtin_amdgcn_global_load_lds((const unsigned*)((const char*)(gbase) + (voff)[_i]), (LAS unsigned*)(lds + (bufoff) + ldsw + _i * 8192), 16, 0, 0); } while (0)
; #define PG8_LDA(dst, b, h) do { _Pragma("unroll") for (int m = 0; m < 4; ++m) _Pragma("unroll") for (int k = 0; k < 2; ++k) dst[m][k] = *(const LAS bf16x8*)(lds + PG8_SA(b, h) + aoff + m * 2048 + k * 1024); } while (0)
; #define PG8_MMA(ai, bj, At, Bt) do { __builtin_amdgcn_s_setprio(1); _Pragma("unroll") for (int m = 0; m < 4; ++m) _Pragma("unroll") for (int n = 0; n < 2; ++n) _Pragma("unroll") for (int k = 0; k < 2; ++k) \
;         acc[ai][bj][m][n] = __builtin_amdgcn_mfma_f32_16x16x32_bf16(Bt[n][k], At[m][k], acc[ai][bj][m][n], 0, 0, 0); __builtin_amdgcn_s_setprio(0); } while (0)
; #define PG8_WAIT_V(n) asm volatile("s_waitcnt vmcnt(" #n ")" ::: "memory")
; #define PG8_WAIT_L(n) asm volatile("s_waitcnt lgkmcnt(" #n ")" ::: "memory")
; #define PG8_BAR __builtin_amdgcn_s_barrier()
; #define PG8_SCHED __builtin_amdgcn_sched_barrier(0)
; __device__ __forceinline__ void gemm_phase(LAS unsigned char* lds, const Gemm g, const StaticOrder& S, const LAS Epi* Ep, const int tid) {
;     ...
;             PG8_WAIT_V(8); PG8_WAIT_L(0); PG8_BAR; PG8_MMA(0, 0, At, B0); PG8_MMA(0, 1, At, B1); PG8_BAR; PG8_SCHED;
;             PG8_LDA(At, 0, 1); PG8_STAGE(PG8_SB(0, 0), b2, voffB); PG8_STAGE(PG8_SB(0, 1), b2 + hstepB, voffB); PG8_STAGE(PG8_SA(0, 0), a2, voffA);
;             PG8_WAIT_V(8); PG8_WAIT_L(0); PG8_BAR; PG8_MMA(1, 0, At, B0); PG8_MMA(1, 1, At, B1); PG8_BAR; PG8_SCHED;
	s_setprio 1
	s_waitcnt lgkmcnt(0)
	v_mfma_f32_16x16x32_bf16 v[128:131], v[132:135], v[164:167], v[128:131]
	v_mfma_f32_16x16x32_bf16 v[120:123], v[140:143], v[164:167], v[120:123]
	v_mfma_f32_16x16x32_bf16 v[112:115], v[132:135], v[172:175], v[112:115]
	v_mfma_f32_16x16x32_bf16 v[104:107], v[140:143], v[172:175], v[104:107]
	v_mfma_f32_16x16x32_bf16 v[96:99], v[132:135], v[180:183], v[96:99]
	v_mfma_f32_16x16x32_bf16 v[88:91], v[140:143], v[180:183], v[88:91]
	v_mfma_f32_16x16x32_bf16 v[80:83], v[132:135], v[188:191], v[80:83]
	v_mfma_f32_16x16x32_bf16 v[72:75], v[140:143], v[188:191], v[72:75]
	v_mfma_f32_16x16x32_bf16 v[128:131], v[136:139], v[168:171], v[128:131]
	v_mfma_f32_16x16x32_bf16 v[120:123], v[144:147], v[168:171], v[120:123]
	v_mfma_f32_16x16x32_bf16 v[112:115], v[136:139], v[176:179], v[112:115]
	v_mfma_f32_16x16x32_bf16 v[104:107], v[144:147], v[176:179], v[104:107]
	v_mfma_f32_16x16x32_bf16 v[96:99], v[136:139], v[184:187], v[96:99]
	v_mfma_f32_16x16x32_bf16 v[88:91], v[144:147], v[184:187], v[88:91]
	v_mfma_f32_16x16x32_bf16 v[80:83], v[136:139], v[192:195], v[80:83]
	v_mfma_f32_16x16x32_bf16 v[72:75], v[144:147], v[192:195], v[72:75]
	s_setprio 0
	s_setprio 1
	v_mfma_f32_16x16x32_bf16 v[124:127], v[148:151], v[164:167], v[124:127]
	v_mfma_f32_16x16x32_bf16 v[116:119], v[156:159], v[164:167], v[116:119]
	v_mfma_f32_16x16x32_bf16 v[108:111], v[148:151], v[172:175], v[108:111]
	v_mfma_f32_16x16x32_bf16 v[100:103], v[156:159], v[172:175], v[100:103]
	v_mfma_f32_16x16x32_bf16 v[92:95], v[148:151], v[180:183], v[92:95]
	v_mfma_f32_16x16x32_bf16 v[84:87], v[156:159], v[180:183], v[84:87]
	v_mfma_f32_16x16x32_bf16 v[76:79], v[148:151], v[188:191], v[76:79]
	v_mfma_f32_16x16x32_bf16 v[68:71], v[156:159], v[188:191], v[68:71]
	v_mfma_f32_16x16x32_bf16 v[124:127], v[152:155], v[168:171], v[124:127]
	v_mfma_f32_16x16x32_bf16 v[116:119], v[160:163], v[168:171], v[116:119]
	v_mfma_f32_16x16x32_bf16 v[108:111], v[152:155], v[176:179], v[108:111]
	v_mfma_f32_16x16x32_bf16 v[100:103], v[160:163], v[176:179], v[100:103]
	v_mfma_f32_16x16x32_bf16 v[92:95], v[152:155], v[184:187], v[92:95]
	v_mfma_f32_16x16x32_bf16 v[84:87], v[160:163], v[184:187], v[84:87]
	v_mfma_f32_16x16x32_bf16 v[76:79], v[152:155], v[192:195], v[76:79]
	v_mfma_f32_16x16x32_bf16 v[68:71], v[160:163], v[192:195], v[68:71]
	s_setprio 0
	s_barrier
	s_add_i32 s16, s16, s86
	v_lshl_add_u64 v[210:211], s[14:15], 0, v[196:197]
	s_mov_b32 m0, s16
	ds_read_b128 v[164:167], v232 offset:16384
	ds_read_b128 v[168:171], v232 offset:17408
	ds_read_b128 v[172:175], v232 offset:18432
	ds_read_b128 v[176:179], v232 offset:19456
	ds_read_b128 v[180:183], v232 offset:20480
	ds_read_b128 v[184:187], v232 offset:21504
	ds_read_b128 v[188:191], v232 offset:22528
	ds_read_b128 v[192:195], v232 offset:23552
	global_load_lds_dwordx4 v[210:211], off
	s_add_i32 m0, s16, 0x2000
	v_lshl_add_u64 v[212:213], s[14:15], 0, v[200:201]
	s_add_u32 s14, s14, s58
	s_addc_u32 s15, s15, 0
	s_add_i32 s16, s17, s86
	global_load_lds_dwordx4 v[212:213], off
	v_lshl_add_u64 v[214:215], s[14:15], 0, v[196:197]
	s_mov_b32 m0, s16
	v_lshl_add_u64 v[216:217], s[14:15], 0, v[200:201]
	global_load_lds_dwordx4 v[214:215], off
	s_add_i32 m0, s16, 0x2000
	v_lshl_add_u64 v[218:219], s[10:11], 0, v[0:1]
	global_load_lds_dwordx4 v[216:217], off
	s_mov_b32 m0, s87
	v_lshl_add_u64 v[220:221], s[10:11], 0, v[198:199]
	global_load_lds_dwordx4 v[218:219], off
	s_mov_b32 m0, s38
	s_nop 0
	global_load_lds_dwordx4 v[220:221], off
	s_waitcnt vmcnt(8)
	s_waitcnt lgkmcnt(0)
	s_barrier
	s_setprio 1
	s_waitcnt lgkmcnt(0)
	v_mfma_f32_16x16x32_bf16 v[64:67], v[132:135], v[164:167], v[64:67]
	v_mfma_f32_16x16x32_bf16 v[56:59], v[140:143], v[164:167], v[56:59]
	v_mfma_f32_16x16x32_bf16 v[48:51], v[132:135], v[172:175], v[48:51]
	v_mfma_f32_16x16x32_bf16 v[40:43], v[140:143], v[172:175], v[40:43]
	v_mfma_f32_16x16x32_bf16 v[32:35], v[132:135], v[180:183], v[32:35]
	v_mfma_f32_16x16x32_bf16 v[24:27], v[140:143], v[180:183], v[24:27]
	v_mfma_f32_16x16x32_bf16 v[16:19], v[132:135], v[188:191], v[16:19]
	v_mfma_f32_16x16x32_bf16 v[8:11], v[140:143], v[188:191], v[8:11]
	v_mfma_f32_16x16x32_bf16 v[64:67], v[136:139], v[168:171], v[64:67]
	v_mfma_f32_16x16x32_bf16 v[56:59], v[144:147], v[168:171], v[56:59]
	v_mfma_f32_16x16x32_bf16 v[48:51], v[136:139], v[176:179], v[48:51]
	v_mfma_f32_16x16x32_bf16 v[40:43], v[144:147], v[176:179], v[40:43]
	v_mfma_f32_16x16x32_bf16 v[32:35], v[136:139], v[184:187], v[32:35]
	v_mfma_f32_16x16x32_bf16 v[24:27], v[144:147], v[184:187], v[24:27]
	v_mfma_f32_16x16x32_bf16 v[16:19], v[136:139], v[192:195], v[16:19]
	v_mfma_f32_16x16x32_bf16 v[8:11], v[144:147], v[192:195], v[8:11]
	s_setprio 0
	s_setprio 1
	v_mfma_f32_16x16x32_bf16 v[60:63], v[148:151], v[164:167], v[60:63]
	v_mfma_f32_16x16x32_bf16 v[52:55], v[156:159], v[164:167], v[52:55]
	v_mfma_f32_16x16x32_bf16 v[44:47], v[148:151], v[172:175], v[44:47]
	v_mfma_f32_16x16x32_bf16 v[36:39], v[156:159], v[172:175], v[36:39]
	v_mfma_f32_16x16x32_bf16 v[28:31], v[148:151], v[180:183], v[28:31]
	v_mfma_f32_16x16x32_bf16 v[20:23], v[156:159], v[180:183], v[20:23]
	v_mfma_f32_16x16x32_bf16 v[12:15], v[148:151], v[188:191], v[12:15]
	v_mfma_f32_16x16x32_bf16 v[4:7], v[156:159], v[188:191], v[4:7]
	v_mfma_f32_16x16x32_bf16 v[60:63], v[152:155], v[168:171], v[60:63]
	v_mfma_f32_16x16x32_bf16 v[52:55], v[160:163], v[168:171], v[52:55]
	v_mfma_f32_16x16x32_bf16 v[44:47], v[152:155], v[176:179], v[44:47]
	v_mfma_f32_16x16x32_bf16 v[36:39], v[160:163], v[176:179], v[36:39]
	v_mfma_f32_16x16x32_bf16 v[28:31], v[152:155], v[184:187], v[28:31]
	v_mfma_f32_16x16x32_bf16 v[20:23], v[160:163], v[184:187], v[20:23]
	v_mfma_f32_16x16x32_bf16 v[12:15], v[152:155], v[192:195], v[12:15]
	v_mfma_f32_16x16x32_bf16 v[4:7], v[160:163], v[192:195], v[4:7]
	s_setprio 0
	s_barrier
; #define PG8_STAGE(bufoff, gbase, voff) do { _Pragma("unroll") for (int _i = 0; _i < 2; ++_i) \
;         __builtin_amdgcn_global_load_lds((const unsigned*)((const char*)(gbase) + (voff)[_i]), (LAS unsigned*)(lds + (bufoff) + ldsw + _i * 8192), 16, 0, 0); } while (0)
; #define PG8_LDA(dst, b, h) do { _Pragma("unroll") for (int m = 0; m < 4; ++m) _Pragma("unroll") for (int k = 0; k < 2; ++k) dst[m][k] = *(const LAS bf16x8*)(lds + PG8_SA(b, h) + aoff + m * 2048 + k * 1024); } while (0)
; #define PG8_LDB(dst, b, h) do { _Pragma("unroll") for (int n = 0; n < 2; ++n) _Pragma("unroll") for (int k = 0; k < 2; ++k) dst[n][k] = *(const LAS bf16x8*)(lds + PG8_SB(b, h) + boff + n * 2048 + k * 1024); } while (0)
; #define PG8_MMA(ai, bj, At, Bt) do { __builtin_amdgcn_s_setprio(1); _Pragma("unroll") for (int m = 0; m < 4; ++m) _Pragma("unroll") for (int n = 0; n < 2; ++n) _Pragma("unroll") for (int k = 0; k < 2; ++k) \
;         acc[ai][bj][m][n] = __builtin_amdgcn_mfma_f32_16x16x32_bf16(Bt[n][k], At[m][k], acc[ai][bj][m][n], 0, 0, 0); __builtin_amdgcn_s_setprio(0); } while (0)
; #define PG8_WAIT_V(n) asm volatile("s_waitcnt vmcnt(" #n ")" ::: "memory")
; #define PG8_WAIT_L(n) asm volatile("s_waitcnt lgkmcnt(" #n ")" ::: "memory")
; #define PG8_BAR __builtin_amdgcn_s_barrier()
; #define PG8_SCHED __builtin_amdgcn_sched_barrier(0)
; __device__ __forceinline__ void gemm_phase(LAS unsigned char* lds, const Gemm g, const StaticOrder& S, const LAS Epi* Ep, const int tid) {
;     ...
;             PG8_LDB(B0, 1, 0); PG8_LDB(B1, 1, 1); PG8_SCHED; PG8_LDA(At, 1, 0); PG8_STAGE(PG8_SA(0, 1), a2 + hstepA, voffA);
;             PG8_WAIT_V(8); PG8_WAIT_L(0); PG8_BAR; PG8_MMA(0, 0, At, B0); PG8_MMA(0, 1, At, B1); PG8_BAR; PG8_SCHED;
;             PG8_LDA(At, 1, 1); PG8_STAGE(PG8_SB(1, 0), b3, voffB); PG8_STAGE(PG8_SB(1, 1), b3 + hstepB, voffB); PG8_STAGE(PG8_SA(1, 0), a3, voffA);
;             PG8_WAIT_V(8); PG8_WAIT_L(0); PG8_BAR; PG8_MMA(1, 0, At, B0); PG8_MMA(1, 1, At, B1); PG8_BAR; PG8_SCHED;
	s_add_i32 s14, 0, 0x18000
	v_add_u32_e32 v2, s14, v230
	s_add_i32 s15, 0, 0x1c000
	ds_read_b128 v[132:135], v2
	ds_read_b128 v[136:139], v2 offset:1024
	ds_read_b128 v[140:143], v2 offset:2048
	ds_read_b128 v[144:147], v2 offset:3072
	v_add_u32_e32 v2, s15, v230
	ds_read_b128 v[148:151], v2
	ds_read_b128 v[152:155], v2 offset:1024
	ds_read_b128 v[156:159], v2 offset:2048
	ds_read_b128 v[160:163], v2 offset:3072
	s_add_u32 s10, s10, s58
	s_addc_u32 s11, s11, 0
	s_mov_b32 m0, s39
	v_lshl_add_u64 v[222:223], s[10:11], 0, v[0:1]
	ds_read_b128 v[164:167], v232 offset:32768
	ds_read_b128 v[168:171], v232 offset:33792
	ds_read_b128 v[172:175], v232 offset:34816
	ds_read_b128 v[176:179], v232 offset:35840
	ds_read_b128 v[180:183], v232 offset:36864
	ds_read_b128 v[184:187], v232 offset:37888
	ds_read_b128 v[188:191], v232 offset:38912
	ds_read_b128 v[192:195], v232 offset:39936
	global_load_lds_dwordx4 v[222:223], off
	v_lshl_add_u64 v[222:223], s[10:11], 0, v[198:199]
	s_mov_b32 m0, s88
	s_nop 0
	global_load_lds_dwordx4 v[222:223], off
	s_waitcnt vmcnt(8)
	s_waitcnt lgkmcnt(0)
	s_barrier
	s_setprio 1
	s_waitcnt lgkmcnt(0)
	v_mfma_f32_16x16x32_bf16 v[128:131], v[132:135], v[164:167], v[128:131]
	v_mfma_f32_16x16x32_bf16 v[120:123], v[140:143], v[164:167], v[120:123]
	v_mfma_f32_16x16x32_bf16 v[112:115], v[132:135], v[172:175], v[112:115]
	v_mfma_f32_16x16x32_bf16 v[104:107], v[140:143], v[172:175], v[104:107]
	v_mfma_f32_16x16x32_bf16 v[96:99], v[132:135], v[180:183], v[96:99]
	v_mfma_f32_16x16x32_bf16 v[88:91], v[140:143], v[180:183], v[88:91]
	v_mfma_f32_16x16x32_bf16 v[80:83], v[132:135], v[188:191], v[80:83]
	v_mfma_f32_16x16x32_bf16 v[72:75], v[140:143], v[188:191], v[72:75]
	v_mfma_f32_16x16x32_bf16 v[128:131], v[136:139], v[168:171], v[128:131]
	v_mfma_f32_16x16x32_bf16 v[120:123], v[144:147], v[168:171], v[120:123]
	v_mfma_f32_16x16x32_bf16 v[112:115], v[136:139], v[176:179], v[112:115]
	v_mfma_f32_16x16x32_bf16 v[104:107], v[144:147], v[176:179], v[104:107]
	v_mfma_f32_16x16x32_bf16 v[96:99], v[136:139], v[184:187], v[96:99]
	v_mfma_f32_16x16x32_bf16 v[88:91], v[144:147], v[184:187], v[88:91]
	v_mfma_f32_16x16x32_bf16 v[80:83], v[136:139], v[192:195], v[80:83]
	v_mfma_f32_16x16x32_bf16 v[72:75], v[144:147], v[192:195], v[72:75]
	s_setprio 0
	s_setprio 1
	v_mfma_f32_16x16x32_bf16 v[124:127], v[148:151], v[164:167], v[124:127]
	v_mfma_f32_16x16x32_bf16 v[116:119], v[156:159], v[164:167], v[116:119]
	v_mfma_f32_16x16x32_bf16 v[108:111], v[148:151], v[172:175], v[108:111]
	v_mfma_f32_16x16x32_bf16 v[100:103], v[156:159], v[172:175], v[100:103]
	v_mfma_f32_16x16x32_bf16 v[92:95], v[148:151], v[180:183], v[92:95]
	v_mfma_f32_16x16x32_bf16 v[84:87], v[156:159], v[180:183], v[84:87]
	v_mfma_f32_16x16x32_bf16 v[76:79], v[148:151], v[188:191], v[76:79]
	v_mfma_f32_16x16x32_bf16 v[68:71], v[156:159], v[188:191], v[68:71]
	v_mfma_f32_16x16x32_bf16 v[124:127], v[152:155], v[168:171], v[124:127]
	v_mfma_f32_16x16x32_bf16 v[116:119], v[160:163], v[168:171], v[116:119]
	v_mfma_f32_16x16x32_bf16 v[108:111], v[152:155], v[176:179], v[108:111]
	v_mfma_f32_16x16x32_bf16 v[100:103], v[160:163], v[176:179], v[100:103]
	v_mfma_f32_16x16x32_bf16 v[92:95], v[152:155], v[184:187], v[92:95]
	v_mfma_f32_16x16x32_bf16 v[84:87], v[160:163], v[184:187], v[84:87]
	v_mfma_f32_16x16x32_bf16 v[76:79], v[152:155], v[192:195], v[76:79]
	v_mfma_f32_16x16x32_bf16 v[68:71], v[160:163], v[192:195], v[68:71]
	s_setprio 0
	s_barrier
	s_add_i32 s10, s14, s86
	v_lshl_add_u64 v[210:211], v[210:211], 0, s[90:91]
	s_mov_b32 m0, s10
	ds_read_b128 v[164:167], v232 offset:49152
	ds_read_b128 v[168:171], v232 offset:50176
	ds_read_b128 v[172:175], v232 offset:51200
	ds_read_b128 v[176:179], v232 offset:52224
	ds_read_b128 v[180:183], v232 offset:53248
	ds_read_b128 v[184:187], v232 offset:54272
	ds_read_b128 v[188:191], v232 offset:55296
	ds_read_b128 v[192:195], v232 offset:56320
	global_load_lds_dwordx4 v[210:211], off
	v_lshl_add_u64 v[210:211], v[212:213], 0, s[90:91]
	s_add_i32 m0, s10, 0x2000
	s_add_i32 s10, s15, s86
	global_load_lds_dwordx4 v[210:211], off
	v_lshl_add_u64 v[210:211], v[214:215], 0, s[90:91]
	s_mov_b32 m0, s10
	s_nop 0
	global_load_lds_dwordx4 v[210:211], off
	v_lshl_add_u64 v[210:211], v[216:217], 0, s[90:91]
	s_add_i32 m0, s10, 0x2000
	s_nop 0
	global_load_lds_dwordx4 v[210:211], off
	v_lshl_add_u64 v[210:211], v[218:219], 0, s[90:91]
	s_mov_b32 m0, s89
	s_nop 0
	global_load_lds_dwordx4 v[210:211], off
	v_lshl_add_u64 v[210:211], v[220:221], 0, s[90:91]
	s_mov_b32 m0, s36
	s_nop 0
	global_load_lds_dwordx4 v[210:211], off
	s_waitcnt vmcnt(8)
	s_waitcnt lgkmcnt(0)
	s_barrier
; #define LAS __attribute__((address_space(3)))
; __device__ __forceinline__ int rfl(int v) { return __builtin_amdgcn_readfirstlane(v); }
; template <class T> __device__ __forceinline__ T* rflp(T* p) { const unsigned long long v = (unsigned long long)p; const unsigned lo = (unsigned)rfl((int)(unsigned)v), hi = (unsigned)rfl((int)(unsigned)(v >> 32)); return (T*)(((unsigned long long)hi << 32) | lo); }
; #define PG8_MMA(ai, bj, At, Bt) do { __builtin_amdgcn_s_setprio(1); _Pragma("unroll") for (int m = 0; m < 4; ++m) _Pragma("unroll") for (int n = 0; n < 2; ++n) _Pragma("unroll") for (int k = 0; k < 2; ++k) \
;         acc[ai][bj][m][n] = __builtin_amdgcn_mfma_f32_16x16x32_bf16(Bt[n][k], At[m][k], acc[ai][bj][m][n], 0, 0, 0); __builtin_amdgcn_s_setprio(0); } while (0)
; #define PG8_WAIT_V(n) asm volatile("s_waitcnt vmcnt(" #n ")" ::: "memory")
; #define PG8_WAIT_L(n) asm volatile("s_waitcnt lgkmcnt(" #n ")" ::: "memory")
; #define PG8_BAR __builtin_amdgcn_s_barrier()
; #define PG8_SCHED __builtin_amdgcn_sched_barrier(0)
; __device__ __forceinline__ Epi load_epi(const LAS Epi* p) {
;     Epi e; e.ssqf = rflp(p->ssqf); e.mode = rfl(p->mode);
;     ...
;     e.mode = FORCE_MODE;
;     ...
;  e.ssq = rflp(p->ssq); e.outb = rflp(p->outb); e.ldo = rfl(p->ldo); e.hin = rflp(p->hin); e.hout = rflp(p->hout);
;     e.alpha = __builtin_bit_cast(float, rfl(__builtin_bit_cast(int, p->alpha))); e.ssq_out = rflp(p->ssq_out); e.hb = rflp(p->hb); e.halo = rflp(p->halo); e.baf = rflp(p->baf); e.gate = rflp(p->gate); e.hinb = rflp(p->hinb);
;     return e;
; }
; __device__ __forceinline__ void gemm_phase(LAS unsigned char* lds, const Gemm g, const StaticOrder& S, const LAS Epi* Ep, const int tid) {
;     ...
;             PG8_WAIT_V(8); PG8_WAIT_L(0); PG8_BAR; PG8_MMA(1, 0, At, B0); PG8_MMA(1, 1, At, B1); PG8_BAR; PG8_SCHED;
;         }
;         if (wr == 0) PG8_BAR;
;         { const Epi E = load_epi(Ep); E(acc, cur, wr, wc, fr, fq, (LAS f32x4*)(lds + 135168 + (wid * 64 + lane) * 32), cur.pm == rs_pm); rs_pm = cur.pm; }
	s_setprio 1
	s_waitcnt lgkmcnt(0)
	v_mfma_f32_16x16x32_bf16 v[64:67], v[132:135], v[164:167], v[64:67]
	v_mfma_f32_16x16x32_bf16 v[56:59], v[140:143], v[164:167], v[56:59]
	v_mfma_f32_16x16x32_bf16 v[48:51], v[132:135], v[172:175], v[48:51]
	v_mfma_f32_16x16x32_bf16 v[40:43], v[140:143], v[172:175], v[40:43]
	v_mfma_f32_16x16x32_bf16 v[32:35], v[132:135], v[180:183], v[32:35]
	v_mfma_f32_16x16x32_bf16 v[24:27], v[140:143], v[180:183], v[24:27]
	v_mfma_f32_16x16x32_bf16 v[16:19], v[132:135], v[188:191], v[16:19]
	v_mfma_f32_16x16x32_bf16 v[8:11], v[140:143], v[188:191], v[8:11]
	v_mfma_f32_16x16x32_bf16 v[64:67], v[136:139], v[168:171], v[64:67]
	v_mfma_f32_16x16x32_bf16 v[56:59], v[144:147], v[168:171], v[56:59]
	v_mfma_f32_16x16x32_bf16 v[48:51], v[136:139], v[176:179], v[48:51]
	v_mfma_f32_16x16x32_bf16 v[40:43], v[144:147], v[176:179], v[40:43]
	v_mfma_f32_16x16x32_bf16 v[32:35], v[136:139], v[184:187], v[32:35]
	v_mfma_f32_16x16x32_bf16 v[24:27], v[144:147], v[184:187], v[24:27]
	v_mfma_f32_16x16x32_bf16 v[16:19], v[136:139], v[192:195], v[16:19]
	v_mfma_f32_16x16x32_bf16 v[8:11], v[144:147], v[192:195], v[8:11]
	s_setprio 0
	s_setprio 1
	v_mfma_f32_16x16x32_bf16 v[60:63], v[148:151], v[164:167], v[60:63]
	v_mfma_f32_16x16x32_bf16 v[52:55], v[156:159], v[164:167], v[52:55]
	v_mfma_f32_16x16x32_bf16 v[44:47], v[148:151], v[172:175], v[44:47]
	v_mfma_f32_16x16x32_bf16 v[36:39], v[156:159], v[172:175], v[36:39]
	v_mfma_f32_16x16x32_bf16 v[28:31], v[148:151], v[180:183], v[28:31]
	v_mfma_f32_16x16x32_bf16 v[20:23], v[156:159], v[180:183], v[20:23]
	v_mfma_f32_16x16x32_bf16 v[12:15], v[148:151], v[188:191], v[12:15]
	v_mfma_f32_16x16x32_bf16 v[4:7], v[156:159], v[188:191], v[4:7]
	v_mfma_f32_16x16x32_bf16 v[60:63], v[152:155], v[168:171], v[60:63]
	v_mfma_f32_16x16x32_bf16 v[52:55], v[160:163], v[168:171], v[52:55]
	v_mfma_f32_16x16x32_bf16 v[44:47], v[152:155], v[176:179], v[44:47]
	v_mfma_f32_16x16x32_bf16 v[36:39], v[160:163], v[176:179], v[36:39]
	v_mfma_f32_16x16x32_bf16 v[28:31], v[152:155], v[184:187], v[28:31]
	v_mfma_f32_16x16x32_bf16 v[20:23], v[160:163], v[184:187], v[20:23]
	v_mfma_f32_16x16x32_bf16 v[12:15], v[152:155], v[192:195], v[12:15]
	v_mfma_f32_16x16x32_bf16 v[4:7], v[160:163], v[192:195], v[4:7]
	s_setprio 0
	s_barrier
	s_add_u32 s0, s0, 0x100
	s_addc_u32 s1, s1, 0
	s_add_u32 s3, s3, 0x100
	s_addc_u32 s12, s12, 0
	s_cmp_ge_u32 s13, s70
	s_mov_b32 s10, s13
	s_cbranch_scc0 .LBB0_1846
.Lpeel3_exit:
	s_and_b64 vcc, exec, s[4:5]
	s_cbranch_vccz .LBB0_1849
	s_barrier
.LBB0_1849:
	v_mov_b32_e32 v2, s26
	ds_read2_b64 v[132:135], v2 offset1:1
	v_mov_b32_e32 v2, s67
	ds_read_b32 v2, v2
	s_lshl_b32 s74, s2, 8
	s_add_i32 s74, s74, s69
	s_waitcnt lgkmcnt(0)
	v_readfirstlane_b32 s17, v133
	v_readfirstlane_b32 s16, v132
	v_readfirstlane_b32 s75, v2
	v_mov_b32_e32 v2, s27
	ds_read_b64 v[132:133], v2
	v_mov_b32_e32 v2, s28
	ds_read_b32 v2, v2
	v_readfirstlane_b32 s65, v135
	v_readfirstlane_b32 s64, v134
	s_waitcnt lgkmcnt(0)
	v_readfirstlane_b32 s11, v133
	v_readfirstlane_b32 s10, v132
	v_readfirstlane_b32 s85, v2
	v_mov_b32_e32 v2, s30
	ds_read_b32 v2, v2
	s_cmp_lt_i32 s75, 1
	v_or_b32_e32 v210, s74, v229
	s_waitcnt lgkmcnt(0)
	v_readfirstlane_b32 s52, v2
	v_mov_b32_e32 v2, s31
	ds_read_b128 v[132:135], v2
	v_mov_b32_e32 v2, s35
	s_waitcnt lgkmcnt(0)
	v_readfirstlane_b32 s25, v133
	v_readfirstlane_b32 s24, v132
	v_readfirstlane_b32 s21, v135
	v_readfirstlane_b32 s20, v134
	ds_read_b128 v[132:135], v2
	v_mov_b32_e32 v2, s34
	s_waitcnt lgkmcnt(0)
	v_readfirstlane_b32 s13, v135
	v_readfirstlane_b32 s12, v134
	ds_read_b128 v[134:137], v2
	v_readfirstlane_b32 s3, v133
	v_readfirstlane_b32 s48, v132
	s_waitcnt lgkmcnt(0)
	v_readfirstlane_b32 s15, v135
	v_readfirstlane_b32 s14, v134
	v_readfirstlane_b32 s1, v137
	v_readfirstlane_b32 s0, v136
	s_cbranch_scc1 .LBB0_1852
	s_cmp_gt_i32 s75, 1
	s_cbranch_scc0 .LBB0_1853
	s_cmp_lg_u32 s75, 2
	s_mov_b64 s[50:51], -1
	s_cselect_b64 s[18:19], -1, 0
	s_cbranch_execz .LBB0_1854
	s_branch .LBB0_1903
